# GELU select peephole extended to 56 of 64 pairs (same math), snake MFMA order
# speedup vs baseline: 1.0093x; 1.0032x over previous
; __device__ __forceinline__ float dot4(f32x4 v) { return (v[0] * v[0] + v[1] * v[1]) + (v[2] * v[2] + v[3] * v[3]); }
; __device__ __forceinline__ u32x2 pack4(f32x4 v) { u32x2 w; w.x = cvt_pk_bf16(v[0], v[1]); w.y = cvt_pk_bf16(v[2], v[3]); return w; }
; __device__ __forceinline__ f32x4 gelu4(f32x4 v) { f32x2 a = gelu_pk((f32x2){v[0], v[1]}), b = gelu_pk((f32x2){v[2], v[3]}); return (f32x4){a.x, a.y, b.x, b.y}; }
; __device__ __forceinline__ f32x2 gelu_pk(f32x2 v) {
;     const f32x2 av = __builtin_elementwise_abs(v), d = av * 0.2316418882f + 1.0f;
;     f32x2 t; t.x = __builtin_amdgcn_rcpf(d.x); t.y = __builtin_amdgcn_rcpf(d.y);
;     f32x2 q = t * 0.5307027145f + (-0.7265760135f); q = q * t + 0.7107068705f; q = q * t + (-0.142248368f); q = q * t + 0.127414796f; q = q * t;
;     const f32x2 s = (v * v) * (-0.72134752044f);
;     f32x2 e; e.x = __builtin_amdgcn_exp2f(s.x); e.y = __builtin_amdgcn_exp2f(s.y);
;     const f32x2 m = v * (q * e), r = v - m;
;     f32x2 o; o.x = v.x < 0.f ? m.x : r.x; o.y = v.y < 0.f ? m.y : r.y; return o;
; template <int EK>
; __device__ __forceinline__ void epi_tile(const f32x4 (&acc)[2][2][4][2], const Unit& u, int wr, int wc, int fr, int fq, const EpiArgs& E, const LAS float* rt) {
;     ...
;             for (int m = 0; m < 4; ++m) rr[ai][m] = rt[ai * HALF + wr * 64 + m * 16 + fr];
;     ...
;             } else if (EK == EK_GELU) {
;                 const float r = rr[ai][m]; float ss = 0.f;
; #pragma unroll
;                 for (int bj = 0; bj < 2; ++bj) { const int col = u.pn * BM + bj * HALF + wc * 32 + fq * 8;
;                     const f32x4 z0 = gelu4(acc[ai][bj][m][0] * r), z1 = gelu4(acc[ai][bj][m][1] * r); ss += dot4(z0) + dot4(z1);
;                     const u32x2 lo = pack4(z0), hi = pack4(z1);
;                     *(u32x4*)(E.ob + (size_t)row * E.ldb + col) = (u32x4){lo.x, lo.y, hi.x, hi.y}; }
.LBB0_932:
	v_lshl_add_u32 v146, s84, 10, v161
	ds_read2_b32 v[156:157], v146 offset1:16
	ds_read2_b32 v[154:155], v146 offset0:32 offset1:48
	ds_read2_b32 v[152:153], v146 offset0:128 offset1:144
	ds_read2_b32 v[148:149], v146 offset0:160 offset1:176
	v_lshl_add_u32 v150, s22, 8, v1
	s_waitcnt lgkmcnt(0)
	v_pk_mul_f32 v[166:167], v[110:111], v[156:157] op_sel_hi:[1,0]
	v_pk_mul_f32 v[170:171], v[112:113], v[156:157] op_sel_hi:[1,0]
	v_fma_f32 v158, |v166|, s40, 1.0
	v_fma_f32 v159, |v167|, s40, 1.0
	v_pk_mul_f32 v[174:175], v[166:167], v[166:167]
	v_rcp_f32_e32 v168, v158
	v_rcp_f32_e32 v169, v159
	v_mov_b64_e32 v[158:159], s[44:45]
	v_pk_mul_f32 v[174:175], v[174:175], s[58:59] op_sel_hi:[1,0]
	v_pk_fma_f32 v[172:173], v[168:169], s[42:43], v[158:159] op_sel_hi:[1,0,0]
	v_exp_f32_e32 v174, v174
	v_pk_fma_f32 v[172:173], v[168:169], v[172:173], s[52:53] op_sel_hi:[1,1,0]
	v_exp_f32_e32 v175, v175
	v_pk_fma_f32 v[172:173], v[168:169], v[172:173], s[54:55] op_sel_hi:[1,1,0]
	v_pk_fma_f32 v[172:173], v[168:169], v[172:173], s[56:57] op_sel_hi:[1,1,0]
	v_fma_f32 v176, |v170|, s40, 1.0
	v_fma_f32 v177, |v171|, s40, 1.0
	v_pk_mul_f32 v[168:169], v[168:169], v[172:173]
	v_rcp_f32_e32 v176, v176
	v_rcp_f32_e32 v177, v177
	v_pk_mul_f32 v[168:169], v[174:175], v[168:169]
	v_max_f32_e32 v174, 0, v166
	v_max_f32_e32 v175, 0, v167
	v_fma_f32 v165, -|v166|, v168, v174
	v_fma_f32 v166, -|v167|, v169, v175
	v_pk_mul_f32 v[172:173], v[170:171], v[170:171]
	v_pk_mul_f32 v[172:173], v[172:173], s[58:59] op_sel_hi:[1,0]
	v_ashrrev_i32_e32 v151, 31, v150
	v_pk_fma_f32 v[168:169], v[176:177], s[42:43], v[158:159] op_sel_hi:[1,0,0]
	v_exp_f32_e32 v172, v172
	v_pk_fma_f32 v[168:169], v[176:177], v[168:169], s[52:53] op_sel_hi:[1,1,0]
	v_exp_f32_e32 v173, v173
	v_pk_fma_f32 v[168:169], v[176:177], v[168:169], s[54:55] op_sel_hi:[1,1,0]
	v_pk_mul_f32 v[174:175], v[106:107], v[156:157] op_sel_hi:[1,0]
	v_pk_fma_f32 v[168:169], v[176:177], v[168:169], s[56:57] op_sel_hi:[1,1,0]
	v_pk_mul_f32 v[168:169], v[176:177], v[168:169]
	v_fma_f32 v176, |v174|, s40, 1.0
	v_fma_f32 v177, |v175|, s40, 1.0
	v_pk_mul_f32 v[168:169], v[172:173], v[168:169]
	v_rcp_f32_e32 v176, v176
	v_rcp_f32_e32 v177, v177
	v_max_f32_e32 v172, 0, v170
	v_max_f32_e32 v173, 0, v171
	v_fma_f32 v167, -|v170|, v168, v172
	v_fma_f32 v168, -|v171|, v169, v173
	v_pk_mul_f32 v[178:179], v[174:175], v[174:175]
	v_pk_fma_f32 v[170:171], v[176:177], s[42:43], v[158:159] op_sel_hi:[1,0,0]
	v_pk_mul_f32 v[178:179], v[178:179], s[58:59] op_sel_hi:[1,0]
	v_pk_mul_f32 v[172:173], v[108:109], v[156:157] op_sel_hi:[1,0]
	v_pk_fma_f32 v[170:171], v[176:177], v[170:171], s[52:53] op_sel_hi:[1,1,0]
	v_exp_f32_e32 v178, v178
	v_exp_f32_e32 v179, v179
	v_pk_fma_f32 v[170:171], v[176:177], v[170:171], s[54:55] op_sel_hi:[1,1,0]
	v_fma_f32 v180, |v172|, s40, 1.0
	v_fma_f32 v181, |v173|, s40, 1.0
	v_pk_fma_f32 v[170:171], v[176:177], v[170:171], s[56:57] op_sel_hi:[1,1,0]
	v_rcp_f32_e32 v180, v180
	v_rcp_f32_e32 v181, v181
	v_pk_mul_f32 v[170:171], v[176:177], v[170:171]
	v_pk_mul_f32 v[170:171], v[178:179], v[170:171]
	v_pk_mul_f32 v[176:177], v[172:173], v[172:173]
	v_max_f32_e32 v178, 0, v174
	v_max_f32_e32 v179, 0, v175
	v_fma_f32 v169, -|v174|, v170, v178
	v_fma_f32 v170, -|v175|, v171, v179
	v_pk_mul_f32 v[176:177], v[176:177], s[58:59] op_sel_hi:[1,0]
	v_pk_fma_f32 v[174:175], v[180:181], s[42:43], v[158:159] op_sel_hi:[1,0,0]
	v_exp_f32_e32 v176, v176
	v_pk_fma_f32 v[174:175], v[180:181], v[174:175], s[52:53] op_sel_hi:[1,1,0]
	v_exp_f32_e32 v177, v177
	v_pk_fma_f32 v[174:175], v[180:181], v[174:175], s[54:55] op_sel_hi:[1,1,0]
	v_lshl_or_b32 v146, s26, 8, v162
	v_pk_fma_f32 v[174:175], v[180:181], v[174:175], s[56:57] op_sel_hi:[1,1,0]
	v_pk_mul_f32 v[174:175], v[180:181], v[174:175]
	v_pk_mul_f32 v[180:181], v[78:79], v[156:157] op_sel_hi:[1,0]
	v_pk_mul_f32 v[174:175], v[176:177], v[174:175]
	v_fma_f32 v182, |v180|, s40, 1.0
	v_fma_f32 v183, |v181|, s40, 1.0
	v_rcp_f32_e32 v182, v182
	v_rcp_f32_e32 v183, v183
	v_max_f32_e32 v176, 0, v172
	v_max_f32_e32 v177, 0, v173
	v_fma_f32 v171, -|v172|, v174, v176
	v_fma_f32 v172, -|v173|, v175, v177
	v_lshlrev_b64 v[178:179], 12, v[150:151]
	v_lshl_add_u64 v[178:179], s[64:65], 0, v[178:179]
	v_ashrrev_i32_e32 v147, 31, v146
	v_cvt_pk_bf16_f32 v174, v165, v166
	v_lshl_add_u64 v[184:185], v[146:147], 1, v[178:179]
	v_cvt_pk_bf16_f32 v175, v167, v168
	v_pk_mul_f32 v[178:179], v[180:181], v[180:181]
	v_cvt_pk_bf16_f32 v176, v169, v170
	v_cvt_pk_bf16_f32 v177, v171, v172
	global_store_dwordx4 v[184:185], v[174:177], off
	v_pk_mul_f32 v[178:179], v[178:179], s[58:59] op_sel_hi:[1,0]
	v_cmp_gt_f32_e32 vcc, 0, v180
	v_pk_fma_f32 v[174:175], v[182:183], s[42:43], v[158:159] op_sel_hi:[1,0,0]
	v_pk_mul_f32 v[176:177], v[80:81], v[156:157] op_sel_hi:[1,0]
	v_pk_fma_f32 v[174:175], v[182:183], v[174:175], s[52:53] op_sel_hi:[1,1,0]
	v_exp_f32_e32 v178, v178
	v_exp_f32_e32 v179, v179
	v_pk_fma_f32 v[174:175], v[182:183], v[174:175], s[54:55] op_sel_hi:[1,1,0]
; __device__ __forceinline__ float dot4(f32x4 v) { return (v[0] * v[0] + v[1] * v[1]) + (v[2] * v[2] + v[3] * v[3]); }
; __device__ __forceinline__ u32x2 pack4(f32x4 v) { u32x2 w; w.x = cvt_pk_bf16(v[0], v[1]); w.y = cvt_pk_bf16(v[2], v[3]); return w; }
; __device__ __forceinline__ float quad_sum(float s) { s += __shfl_xor(s, 16); s += __shfl_xor(s, 32); return s; }
; __device__ __forceinline__ f32x4 gelu4(f32x4 v) { f32x2 a = gelu_pk((f32x2){v[0], v[1]}), b = gelu_pk((f32x2){v[2], v[3]}); return (f32x4){a.x, a.y, b.x, b.y}; }
; __device__ __forceinline__ f32x2 gelu_pk(f32x2 v) {
;     const f32x2 av = __builtin_elementwise_abs(v), d = av * 0.2316418882f + 1.0f;
;     f32x2 t; t.x = __builtin_amdgcn_rcpf(d.x); t.y = __builtin_amdgcn_rcpf(d.y);
;     f32x2 q = t * 0.5307027145f + (-0.7265760135f); q = q * t + 0.7107068705f; q = q * t + (-0.142248368f); q = q * t + 0.127414796f; q = q * t;
;     const f32x2 s = (v * v) * (-0.72134752044f);
;     f32x2 e; e.x = __builtin_amdgcn_exp2f(s.x); e.y = __builtin_amdgcn_exp2f(s.y);
;     const f32x2 m = v * (q * e), r = v - m;
;     f32x2 o; o.x = v.x < 0.f ? m.x : r.x; o.y = v.y < 0.f ? m.y : r.y; return o;
; template <int EK>
; __device__ __forceinline__ void epi_tile(const f32x4 (&acc)[2][2][4][2], const Unit& u, int wr, int wc, int fr, int fq, const EpiArgs& E, const LAS float* rt) {
;     ...
;                 for (int bj = 0; bj < 2; ++bj) { const int col = u.pn * BM + bj * HALF + wc * 32 + fq * 8;
;                     const f32x4 z0 = gelu4(acc[ai][bj][m][0] * r), z1 = gelu4(acc[ai][bj][m][1] * r); ss += dot4(z0) + dot4(z1);
;                     const u32x2 lo = pack4(z0), hi = pack4(z1);
;                     *(u32x4*)(E.ob + (size_t)row * E.ldb + col) = (u32x4){lo.x, lo.y, hi.x, hi.y}; }
;                 if (u.pn >= 4) { ss = quad_sum(ss); if (fq == 0) E.stOut[(size_t)row * 16 + (u.pn - 4) * 4 + wc] = ss; }
	v_pk_fma_f32 v[174:175], v[182:183], v[174:175], s[56:57] op_sel_hi:[1,1,0]
	v_fma_f32 v186, |v176|, s40, 1.0
	v_fma_f32 v187, |v177|, s40, 1.0
	v_pk_mul_f32 v[174:175], v[182:183], v[174:175]
	v_rcp_f32_e32 v186, v186
	v_rcp_f32_e32 v187, v187
	v_pk_mul_f32 v[174:175], v[178:179], v[174:175]
	v_pk_mul_f32 v[182:183], v[176:177], v[176:177]
	v_pk_mul_f32 v[178:179], v[180:181], v[174:175]
	v_pk_fma_f32 v[174:175], v[180:181], v[174:175], v[180:181] neg_lo:[1,0,0] neg_hi:[1,0,0]
	s_cmp_gt_i32 s26, 3
	v_cndmask_b32_e32 v173, v174, v178, vcc
	v_cmp_gt_f32_e32 vcc, 0, v181
	v_pk_mul_f32 v[180:181], v[182:183], s[58:59] op_sel_hi:[1,0]
	v_pk_mul_f32 v[182:183], v[74:75], v[156:157] op_sel_hi:[1,0]
	v_cndmask_b32_e32 v174, v175, v179, vcc
	v_pk_fma_f32 v[178:179], v[186:187], s[42:43], v[158:159] op_sel_hi:[1,0,0]
	v_exp_f32_e32 v180, v180
	v_pk_fma_f32 v[178:179], v[186:187], v[178:179], s[52:53] op_sel_hi:[1,1,0]
	v_exp_f32_e32 v181, v181
	v_pk_fma_f32 v[178:179], v[186:187], v[178:179], s[54:55] op_sel_hi:[1,1,0]
	v_pk_fma_f32 v[178:179], v[186:187], v[178:179], s[56:57] op_sel_hi:[1,1,0]
	v_pk_mul_f32 v[188:189], v[182:183], v[182:183]
	v_pk_mul_f32 v[178:179], v[186:187], v[178:179]
	v_fma_f32 v186, |v182|, s40, 1.0
	v_fma_f32 v187, |v183|, s40, 1.0
	v_pk_mul_f32 v[178:179], v[180:181], v[178:179]
	v_rcp_f32_e32 v186, v186
	v_rcp_f32_e32 v187, v187
	v_max_f32_e32 v180, 0, v176
	v_max_f32_e32 v181, 0, v177
	v_fma_f32 v175, -|v176|, v178, v180
	v_fma_f32 v176, -|v177|, v179, v181
	v_pk_mul_f32 v[188:189], v[188:189], s[58:59] op_sel_hi:[1,0]
	v_exp_f32_e32 v188, v188
	v_exp_f32_e32 v189, v189
	v_pk_fma_f32 v[180:181], v[186:187], s[42:43], v[158:159] op_sel_hi:[1,0,0]
	v_pk_mul_f32 v[178:179], v[76:77], v[156:157] op_sel_hi:[1,0]
	v_pk_fma_f32 v[180:181], v[186:187], v[180:181], s[52:53] op_sel_hi:[1,1,0]
	v_pk_fma_f32 v[180:181], v[186:187], v[180:181], s[54:55] op_sel_hi:[1,1,0]
	v_pk_fma_f32 v[180:181], v[186:187], v[180:181], s[56:57] op_sel_hi:[1,1,0]
	v_fma_f32 v190, |v178|, s40, 1.0
	v_fma_f32 v191, |v179|, s40, 1.0
	v_pk_mul_f32 v[180:181], v[186:187], v[180:181]
	v_rcp_f32_e32 v190, v190
	v_rcp_f32_e32 v191, v191
	v_pk_mul_f32 v[180:181], v[188:189], v[180:181]
	v_max_f32_e32 v188, 0, v182
	v_max_f32_e32 v189, 0, v183
	v_fma_f32 v156, -|v182|, v180, v188
	v_fma_f32 v177, -|v183|, v181, v189
	v_pk_mul_f32 v[186:187], v[178:179], v[178:179]
	v_pk_fma_f32 v[158:159], v[190:191], s[42:43], v[158:159] op_sel_hi:[1,0,0]
	s_cselect_b64 s[78:79], -1, 0
	v_pk_mul_f32 v[180:181], v[186:187], s[58:59] op_sel_hi:[1,0]
	v_pk_fma_f32 v[158:159], v[190:191], v[158:159], s[52:53] op_sel_hi:[1,1,0]
	v_exp_f32_e32 v180, v180
	v_exp_f32_e32 v181, v181
	v_pk_fma_f32 v[158:159], v[190:191], v[158:159], s[54:55] op_sel_hi:[1,1,0]
	s_lshl_b32 s10, s26, 2
	v_pk_fma_f32 v[158:159], v[190:191], v[158:159], s[56:57] op_sel_hi:[1,1,0]
	s_add_i32 s76, s10, -16
	v_pk_mul_f32 v[158:159], v[190:191], v[158:159]
	v_pk_mul_f32 v[158:159], v[180:181], v[158:159]
	s_ashr_i32 s77, s76, 31
	v_max_f32_e32 v180, 0, v178
	v_max_f32_e32 v181, 0, v179
	v_fma_f32 v158, -|v178|, v158, v180
	v_fma_f32 v159, -|v179|, v159, v181
	s_cmp_lt_i32 s26, 4
	v_cvt_pk_bf16_f32 v178, v173, v174
	v_cvt_pk_bf16_f32 v179, v175, v176
	v_cvt_pk_bf16_f32 v180, v156, v177
	s_nop 1
	v_cvt_pk_bf16_f32 v181, v158, v159
	global_store_dwordx4 v[184:185], v[178:181], off offset:256
	s_cbranch_scc1 .LBB0_936
	v_mul_f32_e32 v166, v166, v166
	v_fmac_f32_e32 v166, v165, v165
	v_mul_f32_e32 v165, v168, v168
	v_fmac_f32_e32 v165, v167, v167
	v_add_f32_e32 v165, v166, v165
	v_mul_f32_e32 v166, v170, v170
	v_mul_f32_e32 v167, v172, v172
	v_fmac_f32_e32 v166, v169, v169
	v_fmac_f32_e32 v167, v171, v171
	v_add_f32_e32 v166, v166, v167
	v_add_f32_e32 v165, v165, v166
	v_mul_f32_e32 v166, v174, v174
	v_mul_f32_e32 v167, v176, v176
	v_fmac_f32_e32 v166, v173, v173
	v_fmac_f32_e32 v167, v175, v175
	v_add_f32_e32 v166, v166, v167
	v_mul_f32_e32 v167, v177, v177
	v_fmac_f32_e32 v167, v156, v156
	v_mul_f32_e32 v156, v159, v159
	v_and_b32_e32 v159, 64, v164
	v_fmac_f32_e32 v156, v158, v158
	v_xor_b32_e32 v158, 16, v164
	v_add_u32_e32 v159, 64, v159
	v_add_f32_e32 v156, v167, v156
	v_cmp_lt_i32_e32 vcc, v158, v159
	v_add_f32_e32 v156, v166, v156
	v_add_f32_e32 v156, v165, v156
	v_cndmask_b32_e32 v158, v164, v158, vcc
	v_lshlrev_b32_e32 v158, 2, v158
	ds_bpermute_b32 v158, v158, v156
	s_waitcnt lgkmcnt(0)
	v_add_f32_e32 v156, v156, v158
	v_xor_b32_e32 v158, 32, v164
	v_cmp_lt_i32_e32 vcc, v158, v159
	s_nop 1
	v_cndmask_b32_e32 v158, v164, v158, vcc
	v_lshlrev_b32_e32 v158, 2, v158
	ds_bpermute_b32 v158, v158, v156
	s_and_saveexec_b64 s[10:11], s[4:5]
	s_cbranch_execz .LBB0_935
	v_lshlrev_b64 v[166:167], 6, v[150:151]
	v_lshl_add_u64 v[166:167], s[18:19], 0, v[166:167]
	v_lshl_add_u64 v[166:167], s[76:77], 2, v[166:167]
	s_lshl_b32 s14, s59, 2
	v_lshl_add_u64 v[166:167], v[166:167], 0, s[14:15]
	s_waitcnt lgkmcnt(0)
	v_add_f32_e32 v151, v156, v158
	global_store_dword v[166:167], v151, off

; __device__ __forceinline__ float dot4(f32x4 v) { return (v[0] * v[0] + v[1] * v[1]) + (v[2] * v[2] + v[3] * v[3]); }
; __device__ __forceinline__ u32x2 pack4(f32x4 v) { u32x2 w; w.x = cvt_pk_bf16(v[0], v[1]); w.y = cvt_pk_bf16(v[2], v[3]); return w; }
; __device__ __forceinline__ f32x4 gelu4(f32x4 v) { f32x2 a = gelu_pk((f32x2){v[0], v[1]}), b = gelu_pk((f32x2){v[2], v[3]}); return (f32x4){a.x, a.y, b.x, b.y}; }
; __device__ __forceinline__ f32x2 gelu_pk(f32x2 v) {
;     const f32x2 av = __builtin_elementwise_abs(v), d = av * 0.2316418882f + 1.0f;
;     f32x2 t; t.x = __builtin_amdgcn_rcpf(d.x); t.y = __builtin_amdgcn_rcpf(d.y);
;     f32x2 q = t * 0.5307027145f + (-0.7265760135f); q = q * t + 0.7107068705f; q = q * t + (-0.142248368f); q = q * t + 0.127414796f; q = q * t;
;     const f32x2 s = (v * v) * (-0.72134752044f);
;     f32x2 e; e.x = __builtin_amdgcn_exp2f(s.x); e.y = __builtin_amdgcn_exp2f(s.y);
;     const f32x2 m = v * (q * e), r = v - m;
;     f32x2 o; o.x = v.x < 0.f ? m.x : r.x; o.y = v.y < 0.f ? m.y : r.y; return o;
; template <int EK>
; __device__ __forceinline__ void epi_tile(const f32x4 (&acc)[2][2][4][2], const Unit& u, int wr, int wc, int fr, int fq, const EpiArgs& E, const LAS float* rt) {
;     ...
;             } else if (EK == EK_GELU) {
;                 const float r = rr[ai][m]; float ss = 0.f;
; #pragma unroll
;                 for (int bj = 0; bj < 2; ++bj) { const int col = u.pn * BM + bj * HALF + wc * 32 + fq * 8;
;                     const f32x4 z0 = gelu4(acc[ai][bj][m][0] * r), z1 = gelu4(acc[ai][bj][m][1] * r); ss += dot4(z0) + dot4(z1);
;                     const u32x2 lo = pack4(z0), hi = pack4(z1);
;                     *(u32x4*)(E.ob + (size_t)row * E.ldb + col) = (u32x4){lo.x, lo.y, hi.x, hi.y}; }
.LBB0_936:
	v_mov_b32_e32 v176, v157
	v_pk_mul_f32 v[166:167], v[102:103], v[176:177] op_sel_hi:[1,0]
	v_pk_mul_f32 v[170:171], v[104:105], v[176:177] op_sel_hi:[1,0]
	s_waitcnt lgkmcnt(0)
	v_fma_f32 v158, |v166|, s40, 1.0
	v_fma_f32 v159, |v167|, s40, 1.0
	v_pk_mul_f32 v[174:175], v[166:167], v[166:167]
	v_rcp_f32_e32 v168, v158
	v_rcp_f32_e32 v169, v159
	v_mov_b64_e32 v[158:159], s[44:45]
	v_pk_mul_f32 v[174:175], v[174:175], s[58:59] op_sel_hi:[1,0]
	v_pk_fma_f32 v[172:173], v[168:169], s[42:43], v[158:159] op_sel_hi:[1,0,0]
	v_exp_f32_e32 v174, v174
	v_pk_fma_f32 v[172:173], v[168:169], v[172:173], s[52:53] op_sel_hi:[1,1,0]
	v_exp_f32_e32 v175, v175
	v_pk_fma_f32 v[172:173], v[168:169], v[172:173], s[54:55] op_sel_hi:[1,1,0]
	v_pk_fma_f32 v[172:173], v[168:169], v[172:173], s[56:57] op_sel_hi:[1,1,0]
	v_fma_f32 v178, |v170|, s40, 1.0
	v_fma_f32 v179, |v171|, s40, 1.0
	v_pk_mul_f32 v[168:169], v[168:169], v[172:173]
	v_rcp_f32_e32 v178, v178
	v_rcp_f32_e32 v179, v179
	v_pk_mul_f32 v[168:169], v[174:175], v[168:169]
	v_max_f32_e32 v174, 0, v166
	v_max_f32_e32 v175, 0, v167
	v_fma_f32 v151, -|v166|, v168, v174
	v_fma_f32 v165, -|v167|, v169, v175
	v_pk_mul_f32 v[172:173], v[170:171], v[170:171]
	v_pk_fma_f32 v[166:167], v[178:179], s[42:43], v[158:159] op_sel_hi:[1,0,0]
	v_or_b32_e32 v156, 16, v150
	v_pk_mul_f32 v[168:169], v[172:173], s[58:59] op_sel_hi:[1,0]
	v_pk_fma_f32 v[166:167], v[178:179], v[166:167], s[52:53] op_sel_hi:[1,1,0]
	v_exp_f32_e32 v168, v168
	v_exp_f32_e32 v169, v169
	v_pk_mul_f32 v[172:173], v[98:99], v[176:177] op_sel_hi:[1,0]
	v_pk_fma_f32 v[166:167], v[178:179], v[166:167], s[54:55] op_sel_hi:[1,1,0]
	v_pk_fma_f32 v[166:167], v[178:179], v[166:167], s[56:57] op_sel_hi:[1,1,0]
	v_fma_f32 v174, |v172|, s40, 1.0
	v_fma_f32 v175, |v173|, s40, 1.0
	v_pk_mul_f32 v[166:167], v[178:179], v[166:167]
	v_rcp_f32_e32 v174, v174
	v_rcp_f32_e32 v175, v175
	v_pk_mul_f32 v[166:167], v[168:169], v[166:167]
	v_max_f32_e32 v168, 0, v170
	v_max_f32_e32 v169, 0, v171
	v_fma_f32 v166, -|v170|, v166, v168
	v_fma_f32 v167, -|v171|, v167, v169
	v_pk_mul_f32 v[178:179], v[172:173], v[172:173]
	v_pk_mul_f32 v[170:171], v[100:101], v[176:177] op_sel_hi:[1,0]
	v_pk_mul_f32 v[178:179], v[178:179], s[58:59] op_sel_hi:[1,0]
	v_pk_fma_f32 v[168:169], v[174:175], s[42:43], v[158:159] op_sel_hi:[1,0,0]
	v_exp_f32_e32 v178, v178
	v_pk_fma_f32 v[168:169], v[174:175], v[168:169], s[52:53] op_sel_hi:[1,1,0]
	v_exp_f32_e32 v179, v179
	v_pk_fma_f32 v[168:169], v[174:175], v[168:169], s[54:55] op_sel_hi:[1,1,0]
	v_fma_f32 v180, |v170|, s40, 1.0
	v_fma_f32 v181, |v171|, s40, 1.0
	v_pk_fma_f32 v[168:169], v[174:175], v[168:169], s[56:57] op_sel_hi:[1,1,0]
	v_rcp_f32_e32 v180, v180
	v_rcp_f32_e32 v181, v181
	v_pk_mul_f32 v[168:169], v[174:175], v[168:169]
	v_pk_mul_f32 v[168:169], v[178:179], v[168:169]
	v_pk_mul_f32 v[174:175], v[170:171], v[170:171]
	v_max_f32_e32 v178, 0, v172
	v_max_f32_e32 v179, 0, v173
	v_fma_f32 v168, -|v172|, v168, v178
	v_fma_f32 v169, -|v173|, v169, v179
	v_pk_mul_f32 v[174:175], v[174:175], s[58:59] op_sel_hi:[1,0]
	v_pk_fma_f32 v[172:173], v[180:181], s[42:43], v[158:159] op_sel_hi:[1,0,0]
	v_exp_f32_e32 v174, v174
	v_pk_fma_f32 v[172:173], v[180:181], v[172:173], s[52:53] op_sel_hi:[1,1,0]
	v_exp_f32_e32 v175, v175
	v_pk_fma_f32 v[172:173], v[180:181], v[172:173], s[54:55] op_sel_hi:[1,1,0]
	v_ashrrev_i32_e32 v157, 31, v156
	v_pk_fma_f32 v[172:173], v[180:181], v[172:173], s[56:57] op_sel_hi:[1,1,0]
	v_pk_mul_f32 v[172:173], v[180:181], v[172:173]
	v_pk_mul_f32 v[180:181], v[70:71], v[176:177] op_sel_hi:[1,0]
	v_pk_mul_f32 v[172:173], v[174:175], v[172:173]
	v_fma_f32 v182, |v180|, s40, 1.0
	v_fma_f32 v183, |v181|, s40, 1.0
	v_rcp_f32_e32 v182, v182
	v_rcp_f32_e32 v183, v183
	v_max_f32_e32 v174, 0, v170
	v_max_f32_e32 v175, 0, v171
	v_fma_f32 v170, -|v170|, v172, v174
	v_fma_f32 v171, -|v171|, v173, v175
	v_lshlrev_b64 v[178:179], 12, v[156:157]
	v_lshl_add_u64 v[178:179], s[64:65], 0, v[178:179]
	v_cvt_pk_bf16_f32 v172, v151, v165
	v_lshl_add_u64 v[184:185], v[146:147], 1, v[178:179]
	v_pk_mul_f32 v[178:179], v[180:181], v[180:181]
	v_cvt_pk_bf16_f32 v173, v166, v167
	v_cvt_pk_bf16_f32 v174, v168, v169
	v_cvt_pk_bf16_f32 v175, v170, v171
	global_store_dwordx4 v[184:185], v[172:175], off
	v_pk_mul_f32 v[178:179], v[178:179], s[58:59] op_sel_hi:[1,0]
	v_cmp_gt_f32_e32 vcc, 0, v180
	v_pk_fma_f32 v[172:173], v[182:183], s[42:43], v[158:159] op_sel_hi:[1,0,0]
	v_pk_mul_f32 v[174:175], v[72:73], v[176:177] op_sel_hi:[1,0]
	v_pk_fma_f32 v[172:173], v[182:183], v[172:173], s[52:53] op_sel_hi:[1,1,0]
	v_exp_f32_e32 v178, v178
	v_exp_f32_e32 v179, v179
	v_pk_fma_f32 v[172:173], v[182:183], v[172:173], s[54:55] op_sel_hi:[1,1,0]
	v_pk_fma_f32 v[172:173], v[182:183], v[172:173], s[56:57] op_sel_hi:[1,1,0]
	v_fma_f32 v186, |v174|, s40, 1.0
	v_fma_f32 v187, |v175|, s40, 1.0
; __device__ __forceinline__ float dot4(f32x4 v) { return (v[0] * v[0] + v[1] * v[1]) + (v[2] * v[2] + v[3] * v[3]); }
; __device__ __forceinline__ u32x2 pack4(f32x4 v) { u32x2 w; w.x = cvt_pk_bf16(v[0], v[1]); w.y = cvt_pk_bf16(v[2], v[3]); return w; }
; __device__ __forceinline__ float quad_sum(float s) { s += __shfl_xor(s, 16); s += __shfl_xor(s, 32); return s; }
; __device__ __forceinline__ f32x4 gelu4(f32x4 v) { f32x2 a = gelu_pk((f32x2){v[0], v[1]}), b = gelu_pk((f32x2){v[2], v[3]}); return (f32x4){a.x, a.y, b.x, b.y}; }
; __device__ __forceinline__ f32x2 gelu_pk(f32x2 v) {
;     const f32x2 av = __builtin_elementwise_abs(v), d = av * 0.2316418882f + 1.0f;
;     f32x2 t; t.x = __builtin_amdgcn_rcpf(d.x); t.y = __builtin_amdgcn_rcpf(d.y);
;     f32x2 q = t * 0.5307027145f + (-0.7265760135f); q = q * t + 0.7107068705f; q = q * t + (-0.142248368f); q = q * t + 0.127414796f; q = q * t;
;     const f32x2 s = (v * v) * (-0.72134752044f);
;     f32x2 e; e.x = __builtin_amdgcn_exp2f(s.x); e.y = __builtin_amdgcn_exp2f(s.y);
;     const f32x2 m = v * (q * e), r = v - m;
;     f32x2 o; o.x = v.x < 0.f ? m.x : r.x; o.y = v.y < 0.f ? m.y : r.y; return o;
; template <int EK>
; __device__ __forceinline__ void epi_tile(const f32x4 (&acc)[2][2][4][2], const Unit& u, int wr, int wc, int fr, int fq, const EpiArgs& E, const LAS float* rt) {
;     ...
;                 for (int bj = 0; bj < 2; ++bj) { const int col = u.pn * BM + bj * HALF + wc * 32 + fq * 8;
;                     const f32x4 z0 = gelu4(acc[ai][bj][m][0] * r), z1 = gelu4(acc[ai][bj][m][1] * r); ss += dot4(z0) + dot4(z1);
;                     const u32x2 lo = pack4(z0), hi = pack4(z1);
;                     *(u32x4*)(E.ob + (size_t)row * E.ldb + col) = (u32x4){lo.x, lo.y, hi.x, hi.y}; }
;                 if (u.pn >= 4) { ss = quad_sum(ss); if (fq == 0) E.stOut[(size_t)row * 16 + (u.pn - 4) * 4 + wc] = ss; }
	v_pk_mul_f32 v[172:173], v[182:183], v[172:173]
	v_rcp_f32_e32 v186, v186
	v_rcp_f32_e32 v187, v187
	v_pk_mul_f32 v[172:173], v[178:179], v[172:173]
	v_pk_mul_f32 v[182:183], v[174:175], v[174:175]
	v_pk_mul_f32 v[178:179], v[180:181], v[172:173]
	v_pk_fma_f32 v[172:173], v[180:181], v[172:173], v[180:181] neg_lo:[1,0,0] neg_hi:[1,0,0]
	s_nop 0
	v_cndmask_b32_e32 v172, v172, v178, vcc
	v_cmp_gt_f32_e32 vcc, 0, v181
	v_pk_mul_f32 v[180:181], v[182:183], s[58:59] op_sel_hi:[1,0]
	v_pk_mul_f32 v[182:183], v[66:67], v[176:177] op_sel_hi:[1,0]
	v_cndmask_b32_e32 v173, v173, v179, vcc
	v_pk_fma_f32 v[178:179], v[186:187], s[42:43], v[158:159] op_sel_hi:[1,0,0]
	v_exp_f32_e32 v180, v180
	v_pk_fma_f32 v[178:179], v[186:187], v[178:179], s[52:53] op_sel_hi:[1,1,0]
	v_exp_f32_e32 v181, v181
	v_pk_fma_f32 v[178:179], v[186:187], v[178:179], s[54:55] op_sel_hi:[1,1,0]
	v_pk_fma_f32 v[178:179], v[186:187], v[178:179], s[56:57] op_sel_hi:[1,1,0]
	s_nop 0
	v_pk_mul_f32 v[178:179], v[186:187], v[178:179]
	v_fma_f32 v186, |v182|, s40, 1.0
	v_fma_f32 v187, |v183|, s40, 1.0
	v_pk_mul_f32 v[178:179], v[180:181], v[178:179]
	v_rcp_f32_e32 v186, v186
	v_rcp_f32_e32 v187, v187
	v_max_f32_e32 v180, 0, v174
	v_max_f32_e32 v181, 0, v175
	v_fma_f32 v174, -|v174|, v178, v180
	v_fma_f32 v175, -|v175|, v179, v181
	s_nop 0
	s_nop 1
	v_pk_mul_f32 v[180:181], v[182:183], v[182:183]
	v_pk_mul_f32 v[178:179], v[68:69], v[176:177] op_sel_hi:[1,0]
	v_pk_fma_f32 v[176:177], v[186:187], s[42:43], v[158:159] op_sel_hi:[1,0,0]
	v_pk_mul_f32 v[180:181], v[180:181], s[58:59] op_sel_hi:[1,0]
	v_pk_fma_f32 v[176:177], v[186:187], v[176:177], s[52:53] op_sel_hi:[1,1,0]
	v_exp_f32_e32 v180, v180
	v_exp_f32_e32 v181, v181
	v_pk_fma_f32 v[176:177], v[186:187], v[176:177], s[54:55] op_sel_hi:[1,1,0]
	v_pk_fma_f32 v[176:177], v[186:187], v[176:177], s[56:57] op_sel_hi:[1,1,0]
	v_fma_f32 v188, |v178|, s40, 1.0
	v_fma_f32 v189, |v179|, s40, 1.0
	v_pk_mul_f32 v[176:177], v[186:187], v[176:177]
	v_rcp_f32_e32 v188, v188
	v_rcp_f32_e32 v189, v189
	v_pk_mul_f32 v[176:177], v[180:181], v[176:177]
	v_max_f32_e32 v180, 0, v182
	v_max_f32_e32 v181, 0, v183
	v_fma_f32 v176, -|v182|, v176, v180
	v_fma_f32 v177, -|v183|, v177, v181
	v_pk_mul_f32 v[186:187], v[178:179], v[178:179]
	v_pk_fma_f32 v[158:159], v[188:189], s[42:43], v[158:159] op_sel_hi:[1,0,0]
	v_cndmask_b32_e64 v182, 0, 1, s[78:79]
	v_pk_mul_f32 v[180:181], v[186:187], s[58:59] op_sel_hi:[1,0]
	v_pk_fma_f32 v[158:159], v[188:189], v[158:159], s[52:53] op_sel_hi:[1,1,0]
	v_exp_f32_e32 v180, v180
	v_exp_f32_e32 v181, v181
	v_pk_fma_f32 v[158:159], v[188:189], v[158:159], s[54:55] op_sel_hi:[1,1,0]
	v_pk_fma_f32 v[158:159], v[188:189], v[158:159], s[56:57] op_sel_hi:[1,1,0]
	v_cmp_ne_u32_e64 s[10:11], 1, v182
	v_pk_mul_f32 v[158:159], v[188:189], v[158:159]
	s_nop 0
	v_pk_mul_f32 v[158:159], v[180:181], v[158:159]
	s_nop 0
	v_max_f32_e32 v180, 0, v178
	v_max_f32_e32 v181, 0, v179
	v_fma_f32 v158, -|v178|, v158, v180
	v_fma_f32 v159, -|v179|, v159, v181
	v_cvt_pk_bf16_f32 v178, v172, v173
	s_nop 0
	v_cvt_pk_bf16_f32 v179, v174, v175
	v_cvt_pk_bf16_f32 v180, v176, v177
	s_nop 1
	s_andn2_b64 vcc, exec, s[78:79]
	v_cvt_pk_bf16_f32 v181, v158, v159
	global_store_dwordx4 v[184:185], v[178:181], off offset:256
	s_cbranch_vccnz .LBB0_940
	v_mul_f32_e32 v165, v165, v165
	v_fmac_f32_e32 v165, v151, v151
	v_mul_f32_e32 v151, v167, v167
	v_fmac_f32_e32 v151, v166, v166
	v_add_f32_e32 v151, v165, v151
	v_mul_f32_e32 v165, v169, v169
	v_mul_f32_e32 v166, v171, v171
	v_fmac_f32_e32 v165, v168, v168
	v_fmac_f32_e32 v166, v170, v170
	v_add_f32_e32 v165, v165, v166
	v_add_f32_e32 v151, v151, v165
	v_mul_f32_e32 v165, v173, v173
	v_mul_f32_e32 v166, v175, v175
	v_fmac_f32_e32 v165, v172, v172
	v_fmac_f32_e32 v166, v174, v174
	v_add_f32_e32 v165, v165, v166
	v_mul_f32_e32 v166, v177, v177
	v_mul_f32_e32 v159, v159, v159
	v_fmac_f32_e32 v166, v176, v176
	v_fmac_f32_e32 v159, v158, v158
	v_add_f32_e32 v158, v166, v159
	v_add_f32_e32 v158, v165, v158
	v_and_b32_e32 v159, 64, v164
	v_add_f32_e32 v151, v151, v158
	v_xor_b32_e32 v158, 16, v164
	v_add_u32_e32 v159, 64, v159
	v_cmp_lt_i32_e32 vcc, v158, v159
	s_nop 1
	v_cndmask_b32_e32 v158, v164, v158, vcc
	v_lshlrev_b32_e32 v158, 2, v158
	ds_bpermute_b32 v158, v158, v151
	s_waitcnt lgkmcnt(0)
	v_add_f32_e32 v151, v151, v158
	v_xor_b32_e32 v158, 32, v164
	v_cmp_lt_i32_e32 vcc, v158, v159
	s_nop 1
	v_cndmask_b32_e32 v158, v164, v158, vcc
	v_lshlrev_b32_e32 v158, 2, v158
	ds_bpermute_b32 v158, v158, v151
	s_and_saveexec_b64 s[78:79], s[4:5]
	s_cbranch_execz .LBB0_939
	v_lshlrev_b64 v[156:157], 6, v[156:157]
	v_lshl_add_u64 v[156:157], s[18:19], 0, v[156:157]
	v_lshl_add_u64 v[156:157], s[76:77], 2, v[156:157]
	s_lshl_b32 s14, s59, 2
	v_lshl_add_u64 v[156:157], v[156:157], 0, s[14:15]
	s_waitcnt lgkmcnt(0)
	v_add_f32_e32 v151, v151, v158
	global_store_dword v[156:157], v151, off

; __device__ __forceinline__ float dot4(f32x4 v) { return (v[0] * v[0] + v[1] * v[1]) + (v[2] * v[2] + v[3] * v[3]); }
; __device__ __forceinline__ u32x2 pack4(f32x4 v) { u32x2 w; w.x = cvt_pk_bf16(v[0], v[1]); w.y = cvt_pk_bf16(v[2], v[3]); return w; }
; __device__ __forceinline__ f32x4 gelu4(f32x4 v) { f32x2 a = gelu_pk((f32x2){v[0], v[1]}), b = gelu_pk((f32x2){v[2], v[3]}); return (f32x4){a.x, a.y, b.x, b.y}; }
; __device__ __forceinline__ f32x2 gelu_pk(f32x2 v) {
;     const f32x2 av = __builtin_elementwise_abs(v), d = av * 0.2316418882f + 1.0f;
;     f32x2 t; t.x = __builtin_amdgcn_rcpf(d.x); t.y = __builtin_amdgcn_rcpf(d.y);
;     f32x2 q = t * 0.5307027145f + (-0.7265760135f); q = q * t + 0.7107068705f; q = q * t + (-0.142248368f); q = q * t + 0.127414796f; q = q * t;
;     const f32x2 s = (v * v) * (-0.72134752044f);
;     f32x2 e; e.x = __builtin_amdgcn_exp2f(s.x); e.y = __builtin_amdgcn_exp2f(s.y);
;     const f32x2 m = v * (q * e), r = v - m;
;     f32x2 o; o.x = v.x < 0.f ? m.x : r.x; o.y = v.y < 0.f ? m.y : r.y; return o;
; template <int EK>
; __device__ __forceinline__ void epi_tile(const f32x4 (&acc)[2][2][4][2], const Unit& u, int wr, int wc, int fr, int fq, const EpiArgs& E, const LAS float* rt) {
;     ...
;             } else if (EK == EK_GELU) {
;                 const float r = rr[ai][m]; float ss = 0.f;
; #pragma unroll
;                 for (int bj = 0; bj < 2; ++bj) { const int col = u.pn * BM + bj * HALF + wc * 32 + fq * 8;
;                     const f32x4 z0 = gelu4(acc[ai][bj][m][0] * r), z1 = gelu4(acc[ai][bj][m][1] * r); ss += dot4(z0) + dot4(z1);
;                     const u32x2 lo = pack4(z0), hi = pack4(z1);
;                     *(u32x4*)(E.ob + (size_t)row * E.ldb + col) = (u32x4){lo.x, lo.y, hi.x, hi.y}; }
.LBB0_940:
	v_pk_mul_f32 v[166:167], v[94:95], v[154:155] op_sel_hi:[1,0]
	v_pk_mul_f32 v[170:171], v[96:97], v[154:155] op_sel_hi:[1,0]
	s_waitcnt lgkmcnt(0)
	v_fma_f32 v158, |v166|, s40, 1.0
	v_fma_f32 v159, |v167|, s40, 1.0
	v_pk_mul_f32 v[174:175], v[166:167], v[166:167]
	v_rcp_f32_e32 v168, v158
	v_rcp_f32_e32 v169, v159
	v_mov_b64_e32 v[158:159], s[44:45]
	v_pk_mul_f32 v[174:175], v[174:175], s[58:59] op_sel_hi:[1,0]
	v_pk_fma_f32 v[172:173], v[168:169], s[42:43], v[158:159] op_sel_hi:[1,0,0]
	v_exp_f32_e32 v174, v174
	v_pk_fma_f32 v[172:173], v[168:169], v[172:173], s[52:53] op_sel_hi:[1,1,0]
	v_exp_f32_e32 v175, v175
	v_pk_fma_f32 v[172:173], v[168:169], v[172:173], s[54:55] op_sel_hi:[1,1,0]
	v_pk_fma_f32 v[172:173], v[168:169], v[172:173], s[56:57] op_sel_hi:[1,1,0]
	v_fma_f32 v176, |v170|, s40, 1.0
	v_fma_f32 v177, |v171|, s40, 1.0
	v_pk_mul_f32 v[168:169], v[168:169], v[172:173]
	v_rcp_f32_e32 v176, v176
	v_rcp_f32_e32 v177, v177
	v_pk_mul_f32 v[168:169], v[174:175], v[168:169]
	v_max_f32_e32 v174, 0, v166
	v_max_f32_e32 v175, 0, v167
	v_fma_f32 v151, -|v166|, v168, v174
	v_fma_f32 v165, -|v167|, v169, v175
	v_pk_mul_f32 v[172:173], v[170:171], v[170:171]
	v_pk_fma_f32 v[166:167], v[176:177], s[42:43], v[158:159] op_sel_hi:[1,0,0]
	v_or_b32_e32 v156, 32, v150
	v_pk_mul_f32 v[168:169], v[172:173], s[58:59] op_sel_hi:[1,0]
	v_pk_fma_f32 v[166:167], v[176:177], v[166:167], s[52:53] op_sel_hi:[1,1,0]
	v_exp_f32_e32 v168, v168
	v_exp_f32_e32 v169, v169
	v_pk_mul_f32 v[172:173], v[90:91], v[154:155] op_sel_hi:[1,0]
	v_pk_fma_f32 v[166:167], v[176:177], v[166:167], s[54:55] op_sel_hi:[1,1,0]
	v_pk_fma_f32 v[166:167], v[176:177], v[166:167], s[56:57] op_sel_hi:[1,1,0]
	v_fma_f32 v174, |v172|, s40, 1.0
	v_fma_f32 v175, |v173|, s40, 1.0
	v_pk_mul_f32 v[166:167], v[176:177], v[166:167]
	v_rcp_f32_e32 v174, v174
	v_rcp_f32_e32 v175, v175
	v_pk_mul_f32 v[166:167], v[168:169], v[166:167]
	v_max_f32_e32 v168, 0, v170
	v_max_f32_e32 v169, 0, v171
	v_fma_f32 v166, -|v170|, v166, v168
	v_fma_f32 v167, -|v171|, v167, v169
	v_pk_mul_f32 v[176:177], v[172:173], v[172:173]
	v_pk_mul_f32 v[170:171], v[92:93], v[154:155] op_sel_hi:[1,0]
	v_pk_mul_f32 v[176:177], v[176:177], s[58:59] op_sel_hi:[1,0]
	v_pk_fma_f32 v[168:169], v[174:175], s[42:43], v[158:159] op_sel_hi:[1,0,0]
	v_exp_f32_e32 v176, v176
	v_pk_fma_f32 v[168:169], v[174:175], v[168:169], s[52:53] op_sel_hi:[1,1,0]
	v_exp_f32_e32 v177, v177
	v_pk_fma_f32 v[168:169], v[174:175], v[168:169], s[54:55] op_sel_hi:[1,1,0]
	v_fma_f32 v178, |v170|, s40, 1.0
	v_fma_f32 v179, |v171|, s40, 1.0
	v_pk_fma_f32 v[168:169], v[174:175], v[168:169], s[56:57] op_sel_hi:[1,1,0]
	v_rcp_f32_e32 v178, v178
	v_rcp_f32_e32 v179, v179
	v_pk_mul_f32 v[168:169], v[174:175], v[168:169]
	v_pk_mul_f32 v[168:169], v[176:177], v[168:169]
	v_pk_mul_f32 v[174:175], v[170:171], v[170:171]
	v_max_f32_e32 v176, 0, v172
	v_max_f32_e32 v177, 0, v173
	v_fma_f32 v168, -|v172|, v168, v176
	v_fma_f32 v169, -|v173|, v169, v177
	v_pk_mul_f32 v[174:175], v[174:175], s[58:59] op_sel_hi:[1,0]
	v_pk_fma_f32 v[172:173], v[178:179], s[42:43], v[158:159] op_sel_hi:[1,0,0]
	v_exp_f32_e32 v174, v174
	v_pk_fma_f32 v[172:173], v[178:179], v[172:173], s[52:53] op_sel_hi:[1,1,0]
	v_exp_f32_e32 v175, v175
	v_pk_fma_f32 v[172:173], v[178:179], v[172:173], s[54:55] op_sel_hi:[1,1,0]
	v_ashrrev_i32_e32 v157, 31, v156
	v_pk_fma_f32 v[172:173], v[178:179], v[172:173], s[56:57] op_sel_hi:[1,1,0]
	v_pk_mul_f32 v[172:173], v[178:179], v[172:173]
	v_pk_mul_f32 v[178:179], v[62:63], v[154:155] op_sel_hi:[1,0]
	v_pk_mul_f32 v[172:173], v[174:175], v[172:173]
	v_fma_f32 v180, |v178|, s40, 1.0
	v_fma_f32 v181, |v179|, s40, 1.0
	v_rcp_f32_e32 v180, v180
	v_rcp_f32_e32 v181, v181
	v_max_f32_e32 v174, 0, v170
	v_max_f32_e32 v175, 0, v171
	v_fma_f32 v170, -|v170|, v172, v174
	v_fma_f32 v171, -|v171|, v173, v175
	v_lshlrev_b64 v[176:177], 12, v[156:157]
	v_lshl_add_u64 v[176:177], s[64:65], 0, v[176:177]
	v_cvt_pk_bf16_f32 v172, v151, v165
	v_lshl_add_u64 v[182:183], v[146:147], 1, v[176:177]
	v_pk_mul_f32 v[176:177], v[178:179], v[178:179]
	v_cvt_pk_bf16_f32 v173, v166, v167
	v_cvt_pk_bf16_f32 v174, v168, v169
	v_cvt_pk_bf16_f32 v175, v170, v171
	global_store_dwordx4 v[182:183], v[172:175], off
	v_pk_mul_f32 v[176:177], v[176:177], s[58:59] op_sel_hi:[1,0]
	v_cmp_gt_f32_e32 vcc, 0, v178
	v_pk_fma_f32 v[172:173], v[180:181], s[42:43], v[158:159] op_sel_hi:[1,0,0]
	v_pk_mul_f32 v[174:175], v[64:65], v[154:155] op_sel_hi:[1,0]
	v_pk_fma_f32 v[172:173], v[180:181], v[172:173], s[52:53] op_sel_hi:[1,1,0]
	v_exp_f32_e32 v176, v176
	v_exp_f32_e32 v177, v177
	v_pk_fma_f32 v[172:173], v[180:181], v[172:173], s[54:55] op_sel_hi:[1,1,0]
	v_pk_fma_f32 v[172:173], v[180:181], v[172:173], s[56:57] op_sel_hi:[1,1,0]
	v_fma_f32 v184, |v174|, s40, 1.0
; __device__ __forceinline__ float dot4(f32x4 v) { return (v[0] * v[0] + v[1] * v[1]) + (v[2] * v[2] + v[3] * v[3]); }
; __device__ __forceinline__ u32x2 pack4(f32x4 v) { u32x2 w; w.x = cvt_pk_bf16(v[0], v[1]); w.y = cvt_pk_bf16(v[2], v[3]); return w; }
; __device__ __forceinline__ float quad_sum(float s) { s += __shfl_xor(s, 16); s += __shfl_xor(s, 32); return s; }
; __device__ __forceinline__ f32x4 gelu4(f32x4 v) { f32x2 a = gelu_pk((f32x2){v[0], v[1]}), b = gelu_pk((f32x2){v[2], v[3]}); return (f32x4){a.x, a.y, b.x, b.y}; }
; __device__ __forceinline__ f32x2 gelu_pk(f32x2 v) {
;     const f32x2 av = __builtin_elementwise_abs(v), d = av * 0.2316418882f + 1.0f;
;     f32x2 t; t.x = __builtin_amdgcn_rcpf(d.x); t.y = __builtin_amdgcn_rcpf(d.y);
;     f32x2 q = t * 0.5307027145f + (-0.7265760135f); q = q * t + 0.7107068705f; q = q * t + (-0.142248368f); q = q * t + 0.127414796f; q = q * t;
;     const f32x2 s = (v * v) * (-0.72134752044f);
;     f32x2 e; e.x = __builtin_amdgcn_exp2f(s.x); e.y = __builtin_amdgcn_exp2f(s.y);
;     const f32x2 m = v * (q * e), r = v - m;
;     f32x2 o; o.x = v.x < 0.f ? m.x : r.x; o.y = v.y < 0.f ? m.y : r.y; return o;
; template <int EK>
; __device__ __forceinline__ void epi_tile(const f32x4 (&acc)[2][2][4][2], const Unit& u, int wr, int wc, int fr, int fq, const EpiArgs& E, const LAS float* rt) {
;     ...
;                 for (int bj = 0; bj < 2; ++bj) { const int col = u.pn * BM + bj * HALF + wc * 32 + fq * 8;
;                     const f32x4 z0 = gelu4(acc[ai][bj][m][0] * r), z1 = gelu4(acc[ai][bj][m][1] * r); ss += dot4(z0) + dot4(z1);
;                     const u32x2 lo = pack4(z0), hi = pack4(z1);
;                     *(u32x4*)(E.ob + (size_t)row * E.ldb + col) = (u32x4){lo.x, lo.y, hi.x, hi.y}; }
;                 if (u.pn >= 4) { ss = quad_sum(ss); if (fq == 0) E.stOut[(size_t)row * 16 + (u.pn - 4) * 4 + wc] = ss; }
	v_fma_f32 v185, |v175|, s40, 1.0
	v_pk_mul_f32 v[172:173], v[180:181], v[172:173]
	v_rcp_f32_e32 v184, v184
	v_rcp_f32_e32 v185, v185
	v_pk_mul_f32 v[172:173], v[176:177], v[172:173]
	v_pk_mul_f32 v[180:181], v[174:175], v[174:175]
	v_pk_mul_f32 v[176:177], v[178:179], v[172:173]
	v_pk_fma_f32 v[172:173], v[178:179], v[172:173], v[178:179] neg_lo:[1,0,0] neg_hi:[1,0,0]
	s_nop 0
	v_cndmask_b32_e32 v172, v172, v176, vcc
	v_cmp_gt_f32_e32 vcc, 0, v179
	v_pk_mul_f32 v[178:179], v[180:181], s[58:59] op_sel_hi:[1,0]
	v_pk_mul_f32 v[180:181], v[58:59], v[154:155] op_sel_hi:[1,0]
	v_cndmask_b32_e32 v173, v173, v177, vcc
	v_pk_fma_f32 v[176:177], v[184:185], s[42:43], v[158:159] op_sel_hi:[1,0,0]
	v_exp_f32_e32 v178, v178
	v_pk_fma_f32 v[176:177], v[184:185], v[176:177], s[52:53] op_sel_hi:[1,1,0]
	v_exp_f32_e32 v179, v179
	v_pk_fma_f32 v[176:177], v[184:185], v[176:177], s[54:55] op_sel_hi:[1,1,0]
	v_pk_fma_f32 v[176:177], v[184:185], v[176:177], s[56:57] op_sel_hi:[1,1,0]
	v_pk_mul_f32 v[186:187], v[180:181], v[180:181]
	v_pk_mul_f32 v[176:177], v[184:185], v[176:177]
	v_fma_f32 v184, |v180|, s40, 1.0
	v_fma_f32 v185, |v181|, s40, 1.0
	v_pk_mul_f32 v[176:177], v[178:179], v[176:177]
	v_rcp_f32_e32 v184, v184
	v_rcp_f32_e32 v185, v185
	v_max_f32_e32 v178, 0, v174
	v_max_f32_e32 v179, 0, v175
	v_fma_f32 v174, -|v174|, v176, v178
	v_fma_f32 v175, -|v175|, v177, v179
	v_pk_mul_f32 v[186:187], v[186:187], s[58:59] op_sel_hi:[1,0]
	v_exp_f32_e32 v186, v186
	v_exp_f32_e32 v187, v187
	v_pk_mul_f32 v[178:179], v[60:61], v[154:155] op_sel_hi:[1,0]
	v_pk_fma_f32 v[176:177], v[184:185], s[42:43], v[158:159] op_sel_hi:[1,0,0]
	v_pk_fma_f32 v[176:177], v[184:185], v[176:177], s[52:53] op_sel_hi:[1,1,0]
	v_pk_fma_f32 v[176:177], v[184:185], v[176:177], s[54:55] op_sel_hi:[1,1,0]
	v_fma_f32 v188, |v178|, s40, 1.0
	v_fma_f32 v189, |v179|, s40, 1.0
	v_pk_fma_f32 v[176:177], v[184:185], v[176:177], s[56:57] op_sel_hi:[1,1,0]
	v_rcp_f32_e32 v188, v188
	v_rcp_f32_e32 v189, v189
	v_pk_mul_f32 v[176:177], v[184:185], v[176:177]
	v_pk_mul_f32 v[184:185], v[178:179], v[178:179]
	v_pk_mul_f32 v[176:177], v[186:187], v[176:177]
	v_max_f32_e32 v186, 0, v180
	v_max_f32_e32 v187, 0, v181
	v_fma_f32 v154, -|v180|, v176, v186
	v_fma_f32 v176, -|v181|, v177, v187
	v_pk_fma_f32 v[158:159], v[188:189], s[42:43], v[158:159] op_sel_hi:[1,0,0]
	v_pk_mul_f32 v[180:181], v[184:185], s[58:59] op_sel_hi:[1,0]
	v_pk_fma_f32 v[158:159], v[188:189], v[158:159], s[52:53] op_sel_hi:[1,1,0]
	v_exp_f32_e32 v180, v180
	v_exp_f32_e32 v181, v181
	v_pk_fma_f32 v[158:159], v[188:189], v[158:159], s[54:55] op_sel_hi:[1,1,0]
	v_pk_fma_f32 v[158:159], v[188:189], v[158:159], s[56:57] op_sel_hi:[1,1,0]
	v_pk_mul_f32 v[158:159], v[188:189], v[158:159]
	s_nop 0
	v_pk_mul_f32 v[158:159], v[180:181], v[158:159]
	s_nop 0
	v_max_f32_e32 v180, 0, v178
	v_max_f32_e32 v181, 0, v179
	v_fma_f32 v158, -|v178|, v158, v180
	v_fma_f32 v159, -|v179|, v159, v181
	v_cvt_pk_bf16_f32 v178, v172, v173
	s_nop 0
	v_cvt_pk_bf16_f32 v179, v174, v175
	v_cvt_pk_bf16_f32 v180, v154, v176
	s_nop 1
	s_and_b64 vcc, exec, s[10:11]
	v_cvt_pk_bf16_f32 v181, v158, v159
	global_store_dwordx4 v[182:183], v[178:181], off offset:256
	s_cbranch_vccnz .LBB0_944
	v_mul_f32_e32 v165, v165, v165
	v_fmac_f32_e32 v165, v151, v151
	v_mul_f32_e32 v151, v167, v167
	v_fmac_f32_e32 v151, v166, v166
	v_add_f32_e32 v151, v165, v151
	v_mul_f32_e32 v165, v169, v169
	v_mul_f32_e32 v166, v171, v171
	v_fmac_f32_e32 v165, v168, v168
	v_fmac_f32_e32 v166, v170, v170
	v_add_f32_e32 v165, v165, v166
	v_add_f32_e32 v151, v151, v165
	v_mul_f32_e32 v165, v173, v173
	v_mul_f32_e32 v166, v175, v175
	v_fmac_f32_e32 v165, v172, v172
	v_fmac_f32_e32 v166, v174, v174
	v_add_f32_e32 v165, v165, v166
	v_mul_f32_e32 v166, v176, v176
	v_fmac_f32_e32 v166, v154, v154
	v_mul_f32_e32 v154, v159, v159
	v_fmac_f32_e32 v154, v158, v158
	v_add_f32_e32 v154, v166, v154
	v_add_f32_e32 v154, v165, v154
	v_and_b32_e32 v158, 64, v164
	v_add_f32_e32 v151, v151, v154
	v_xor_b32_e32 v154, 16, v164
	v_add_u32_e32 v158, 64, v158
	v_cmp_lt_i32_e32 vcc, v154, v158
	s_nop 1
	v_cndmask_b32_e32 v154, v164, v154, vcc
	v_lshlrev_b32_e32 v154, 2, v154
	ds_bpermute_b32 v154, v154, v151
	s_waitcnt lgkmcnt(0)
	v_add_f32_e32 v151, v151, v154
	v_xor_b32_e32 v154, 32, v164
	v_cmp_lt_i32_e32 vcc, v154, v158
	s_nop 1
	v_cndmask_b32_e32 v154, v164, v154, vcc
	v_lshlrev_b32_e32 v154, 2, v154
	ds_bpermute_b32 v154, v154, v151
	s_and_saveexec_b64 s[78:79], s[4:5]
	s_cbranch_execz .LBB0_943
	v_lshlrev_b64 v[156:157], 6, v[156:157]
	v_lshl_add_u64 v[156:157], s[18:19], 0, v[156:157]
	v_lshl_add_u64 v[156:157], s[76:77], 2, v[156:157]
	s_lshl_b32 s14, s59, 2
	v_lshl_add_u64 v[156:157], v[156:157], 0, s[14:15]
	s_waitcnt lgkmcnt(0)
	v_add_f32_e32 v151, v151, v154
	global_store_dword v[156:157], v151, off

; __device__ __forceinline__ float dot4(f32x4 v) { return (v[0] * v[0] + v[1] * v[1]) + (v[2] * v[2] + v[3] * v[3]); }
; __device__ __forceinline__ u32x2 pack4(f32x4 v) { u32x2 w; w.x = cvt_pk_bf16(v[0], v[1]); w.y = cvt_pk_bf16(v[2], v[3]); return w; }
; __device__ __forceinline__ f32x4 gelu4(f32x4 v) { f32x2 a = gelu_pk((f32x2){v[0], v[1]}), b = gelu_pk((f32x2){v[2], v[3]}); return (f32x4){a.x, a.y, b.x, b.y}; }
; __device__ __forceinline__ f32x2 gelu_pk(f32x2 v) {
;     const f32x2 av = __builtin_elementwise_abs(v), d = av * 0.2316418882f + 1.0f;
;     f32x2 t; t.x = __builtin_amdgcn_rcpf(d.x); t.y = __builtin_amdgcn_rcpf(d.y);
;     f32x2 q = t * 0.5307027145f + (-0.7265760135f); q = q * t + 0.7107068705f; q = q * t + (-0.142248368f); q = q * t + 0.127414796f; q = q * t;
;     const f32x2 s = (v * v) * (-0.72134752044f);
;     f32x2 e; e.x = __builtin_amdgcn_exp2f(s.x); e.y = __builtin_amdgcn_exp2f(s.y);
;     const f32x2 m = v * (q * e), r = v - m;
;     f32x2 o; o.x = v.x < 0.f ? m.x : r.x; o.y = v.y < 0.f ? m.y : r.y; return o;
; template <int EK>
; __device__ __forceinline__ void epi_tile(const f32x4 (&acc)[2][2][4][2], const Unit& u, int wr, int wc, int fr, int fq, const EpiArgs& E, const LAS float* rt) {
;     ...
;             } else if (EK == EK_GELU) {
;                 const float r = rr[ai][m]; float ss = 0.f;
; #pragma unroll
;                 for (int bj = 0; bj < 2; ++bj) { const int col = u.pn * BM + bj * HALF + wc * 32 + fq * 8;
;                     const f32x4 z0 = gelu4(acc[ai][bj][m][0] * r), z1 = gelu4(acc[ai][bj][m][1] * r); ss += dot4(z0) + dot4(z1);
;                     const u32x2 lo = pack4(z0), hi = pack4(z1);
;                     *(u32x4*)(E.ob + (size_t)row * E.ldb + col) = (u32x4){lo.x, lo.y, hi.x, hi.y}; }
.LBB0_944:
	v_mov_b32_e32 v174, v155
	v_pk_mul_f32 v[158:159], v[86:87], v[174:175] op_sel_hi:[1,0]
	v_pk_mul_f32 v[168:169], v[88:89], v[174:175] op_sel_hi:[1,0]
	v_fma_f32 v156, |v158|, s40, 1.0
	v_fma_f32 v157, |v159|, s40, 1.0
	v_pk_mul_f32 v[172:173], v[158:159], v[158:159]
	v_rcp_f32_e32 v166, v156
	v_rcp_f32_e32 v167, v157
	v_mov_b64_e32 v[156:157], s[44:45]
	v_pk_mul_f32 v[172:173], v[172:173], s[58:59] op_sel_hi:[1,0]
	v_pk_fma_f32 v[170:171], v[166:167], s[42:43], v[156:157] op_sel_hi:[1,0,0]
	v_exp_f32_e32 v172, v172
	v_pk_fma_f32 v[170:171], v[166:167], v[170:171], s[52:53] op_sel_hi:[1,1,0]
	v_exp_f32_e32 v173, v173
	v_pk_fma_f32 v[170:171], v[166:167], v[170:171], s[54:55] op_sel_hi:[1,1,0]
	v_pk_fma_f32 v[170:171], v[166:167], v[170:171], s[56:57] op_sel_hi:[1,1,0]
	v_fma_f32 v176, |v168|, s40, 1.0
	v_fma_f32 v177, |v169|, s40, 1.0
	v_pk_mul_f32 v[166:167], v[166:167], v[170:171]
	v_rcp_f32_e32 v176, v176
	v_rcp_f32_e32 v177, v177
	v_pk_mul_f32 v[166:167], v[172:173], v[166:167]
	v_max_f32_e32 v172, 0, v158
	v_max_f32_e32 v173, 0, v159
	v_fma_f32 v151, -|v158|, v166, v172
	v_fma_f32 v158, -|v159|, v167, v173
	v_pk_mul_f32 v[170:171], v[168:169], v[168:169]
	v_pk_mul_f32 v[170:171], v[170:171], s[58:59] op_sel_hi:[1,0]
	s_waitcnt lgkmcnt(0)
	v_or_b32_e32 v154, 48, v150
	v_pk_fma_f32 v[166:167], v[176:177], s[42:43], v[156:157] op_sel_hi:[1,0,0]
	v_exp_f32_e32 v170, v170
	v_pk_fma_f32 v[166:167], v[176:177], v[166:167], s[52:53] op_sel_hi:[1,1,0]
	v_exp_f32_e32 v171, v171
	v_pk_fma_f32 v[166:167], v[176:177], v[166:167], s[54:55] op_sel_hi:[1,1,0]
	v_pk_mul_f32 v[172:173], v[82:83], v[174:175] op_sel_hi:[1,0]
	v_pk_fma_f32 v[166:167], v[176:177], v[166:167], s[56:57] op_sel_hi:[1,1,0]
	v_pk_mul_f32 v[166:167], v[176:177], v[166:167]
	v_fma_f32 v176, |v172|, s40, 1.0
	v_fma_f32 v177, |v173|, s40, 1.0
	v_pk_mul_f32 v[166:167], v[170:171], v[166:167]
	v_rcp_f32_e32 v176, v176
	v_rcp_f32_e32 v177, v177
	v_max_f32_e32 v170, 0, v168
	v_max_f32_e32 v171, 0, v169
	v_fma_f32 v159, -|v168|, v166, v170
	v_fma_f32 v165, -|v169|, v167, v171
	v_ashrrev_i32_e32 v155, 31, v154
	v_pk_mul_f32 v[168:169], v[84:85], v[174:175] op_sel_hi:[1,0]
	s_nop 0
	v_pk_mul_f32 v[170:171], v[172:173], v[172:173]
	v_pk_fma_f32 v[166:167], v[176:177], s[42:43], v[156:157] op_sel_hi:[1,0,0]
	v_pk_mul_f32 v[170:171], v[170:171], s[58:59] op_sel_hi:[1,0]
	v_pk_fma_f32 v[166:167], v[176:177], v[166:167], s[52:53] op_sel_hi:[1,1,0]
	v_exp_f32_e32 v170, v170
	v_exp_f32_e32 v171, v171
	v_pk_fma_f32 v[166:167], v[176:177], v[166:167], s[54:55] op_sel_hi:[1,1,0]
	v_pk_fma_f32 v[166:167], v[176:177], v[166:167], s[56:57] op_sel_hi:[1,1,0]
	v_fma_f32 v178, |v168|, s40, 1.0
	v_fma_f32 v179, |v169|, s40, 1.0
	v_pk_mul_f32 v[166:167], v[176:177], v[166:167]
	v_rcp_f32_e32 v178, v178
	v_rcp_f32_e32 v179, v179
	v_pk_mul_f32 v[166:167], v[170:171], v[166:167]
	v_max_f32_e32 v170, 0, v172
	v_max_f32_e32 v171, 0, v173
	v_fma_f32 v166, -|v172|, v166, v170
	v_fma_f32 v167, -|v173|, v167, v171
	v_pk_mul_f32 v[176:177], v[168:169], v[168:169]
	v_pk_mul_f32 v[172:173], v[176:177], s[58:59] op_sel_hi:[1,0]
	v_lshlrev_b64 v[176:177], 12, v[154:155]
	v_pk_fma_f32 v[170:171], v[178:179], s[42:43], v[156:157] op_sel_hi:[1,0,0]
	v_exp_f32_e32 v172, v172
	v_pk_fma_f32 v[170:171], v[178:179], v[170:171], s[52:53] op_sel_hi:[1,1,0]
	v_exp_f32_e32 v173, v173
	v_pk_fma_f32 v[170:171], v[178:179], v[170:171], s[54:55] op_sel_hi:[1,1,0]
	v_pk_fma_f32 v[170:171], v[178:179], v[170:171], s[56:57] op_sel_hi:[1,1,0]
	v_lshl_add_u64 v[176:177], s[64:65], 0, v[176:177]
	v_pk_mul_f32 v[170:171], v[178:179], v[170:171]
	v_pk_mul_f32 v[178:179], v[54:55], v[174:175] op_sel_hi:[1,0]
	v_pk_mul_f32 v[170:171], v[172:173], v[170:171]
	v_fma_f32 v180, |v178|, s40, 1.0
	v_fma_f32 v181, |v179|, s40, 1.0
	v_rcp_f32_e32 v180, v180
	v_rcp_f32_e32 v181, v181
	v_max_f32_e32 v172, 0, v168
	v_max_f32_e32 v173, 0, v169
	v_fma_f32 v168, -|v168|, v170, v172
	v_fma_f32 v169, -|v169|, v171, v173
	v_lshl_add_u64 v[182:183], v[146:147], 1, v[176:177]
	v_cvt_pk_bf16_f32 v170, v151, v158
	v_pk_mul_f32 v[176:177], v[178:179], v[178:179]
	v_cvt_pk_bf16_f32 v172, v166, v167
	s_nop 0
	v_cvt_pk_bf16_f32 v171, v159, v165
	v_cvt_pk_bf16_f32 v173, v168, v169
	global_store_dwordx4 v[182:183], v[170:173], off
	v_pk_mul_f32 v[176:177], v[176:177], s[58:59] op_sel_hi:[1,0]
	v_cmp_gt_f32_e32 vcc, 0, v178
	v_pk_fma_f32 v[170:171], v[180:181], s[42:43], v[156:157] op_sel_hi:[1,0,0]
	v_pk_mul_f32 v[172:173], v[56:57], v[174:175] op_sel_hi:[1,0]
	v_pk_fma_f32 v[170:171], v[180:181], v[170:171], s[52:53] op_sel_hi:[1,1,0]
	v_exp_f32_e32 v176, v176
	v_exp_f32_e32 v177, v177
	v_pk_fma_f32 v[170:171], v[180:181], v[170:171], s[54:55] op_sel_hi:[1,1,0]
	v_pk_fma_f32 v[170:171], v[180:181], v[170:171], s[56:57] op_sel_hi:[1,1,0]
	v_fma_f32 v184, |v172|, s40, 1.0
; __device__ __forceinline__ float dot4(f32x4 v) { return (v[0] * v[0] + v[1] * v[1]) + (v[2] * v[2] + v[3] * v[3]); }
; __device__ __forceinline__ u32x2 pack4(f32x4 v) { u32x2 w; w.x = cvt_pk_bf16(v[0], v[1]); w.y = cvt_pk_bf16(v[2], v[3]); return w; }
; __device__ __forceinline__ float quad_sum(float s) { s += __shfl_xor(s, 16); s += __shfl_xor(s, 32); return s; }
; __device__ __forceinline__ f32x4 gelu4(f32x4 v) { f32x2 a = gelu_pk((f32x2){v[0], v[1]}), b = gelu_pk((f32x2){v[2], v[3]}); return (f32x4){a.x, a.y, b.x, b.y}; }
; __device__ __forceinline__ f32x2 gelu_pk(f32x2 v) {
;     const f32x2 av = __builtin_elementwise_abs(v), d = av * 0.2316418882f + 1.0f;
;     f32x2 t; t.x = __builtin_amdgcn_rcpf(d.x); t.y = __builtin_amdgcn_rcpf(d.y);
;     f32x2 q = t * 0.5307027145f + (-0.7265760135f); q = q * t + 0.7107068705f; q = q * t + (-0.142248368f); q = q * t + 0.127414796f; q = q * t;
;     const f32x2 s = (v * v) * (-0.72134752044f);
;     f32x2 e; e.x = __builtin_amdgcn_exp2f(s.x); e.y = __builtin_amdgcn_exp2f(s.y);
;     const f32x2 m = v * (q * e), r = v - m;
;     f32x2 o; o.x = v.x < 0.f ? m.x : r.x; o.y = v.y < 0.f ? m.y : r.y; return o;
; template <int EK>
; __device__ __forceinline__ void epi_tile(const f32x4 (&acc)[2][2][4][2], const Unit& u, int wr, int wc, int fr, int fq, const EpiArgs& E, const LAS float* rt) {
;     ...
;                 for (int bj = 0; bj < 2; ++bj) { const int col = u.pn * BM + bj * HALF + wc * 32 + fq * 8;
;                     const f32x4 z0 = gelu4(acc[ai][bj][m][0] * r), z1 = gelu4(acc[ai][bj][m][1] * r); ss += dot4(z0) + dot4(z1);
;                     const u32x2 lo = pack4(z0), hi = pack4(z1);
;                     *(u32x4*)(E.ob + (size_t)row * E.ldb + col) = (u32x4){lo.x, lo.y, hi.x, hi.y}; }
;                 if (u.pn >= 4) { ss = quad_sum(ss); if (fq == 0) E.stOut[(size_t)row * 16 + (u.pn - 4) * 4 + wc] = ss; }
	v_fma_f32 v185, |v173|, s40, 1.0
	v_pk_mul_f32 v[170:171], v[180:181], v[170:171]
	v_rcp_f32_e32 v184, v184
	v_rcp_f32_e32 v185, v185
	v_pk_mul_f32 v[170:171], v[176:177], v[170:171]
	v_pk_mul_f32 v[180:181], v[172:173], v[172:173]
	v_pk_mul_f32 v[176:177], v[178:179], v[170:171]
	v_pk_fma_f32 v[170:171], v[178:179], v[170:171], v[178:179] neg_lo:[1,0,0] neg_hi:[1,0,0]
	s_nop 0
	v_cndmask_b32_e32 v170, v170, v176, vcc
	v_cmp_gt_f32_e32 vcc, 0, v179
	v_pk_mul_f32 v[178:179], v[180:181], s[58:59] op_sel_hi:[1,0]
	v_pk_mul_f32 v[180:181], v[50:51], v[174:175] op_sel_hi:[1,0]
	v_cndmask_b32_e32 v171, v171, v177, vcc
	v_pk_fma_f32 v[176:177], v[184:185], s[42:43], v[156:157] op_sel_hi:[1,0,0]
	v_exp_f32_e32 v178, v178
	v_pk_fma_f32 v[176:177], v[184:185], v[176:177], s[52:53] op_sel_hi:[1,1,0]
	v_exp_f32_e32 v179, v179
	v_pk_fma_f32 v[176:177], v[184:185], v[176:177], s[54:55] op_sel_hi:[1,1,0]
	v_pk_fma_f32 v[176:177], v[184:185], v[176:177], s[56:57] op_sel_hi:[1,1,0]
	s_nop 0
	v_pk_mul_f32 v[176:177], v[184:185], v[176:177]
	v_fma_f32 v184, |v180|, s40, 1.0
	v_fma_f32 v185, |v181|, s40, 1.0
	v_pk_mul_f32 v[176:177], v[178:179], v[176:177]
	v_rcp_f32_e32 v184, v184
	v_rcp_f32_e32 v185, v185
	v_max_f32_e32 v178, 0, v172
	v_max_f32_e32 v179, 0, v173
	v_fma_f32 v172, -|v172|, v176, v178
	v_fma_f32 v173, -|v173|, v177, v179
	s_nop 0
	s_nop 1
	v_pk_mul_f32 v[178:179], v[180:181], v[180:181]
	v_pk_mul_f32 v[176:177], v[52:53], v[174:175] op_sel_hi:[1,0]
	v_pk_fma_f32 v[174:175], v[184:185], s[42:43], v[156:157] op_sel_hi:[1,0,0]
	v_pk_mul_f32 v[178:179], v[178:179], s[58:59] op_sel_hi:[1,0]
	v_pk_fma_f32 v[174:175], v[184:185], v[174:175], s[52:53] op_sel_hi:[1,1,0]
	v_exp_f32_e32 v178, v178
	v_exp_f32_e32 v179, v179
	v_pk_fma_f32 v[174:175], v[184:185], v[174:175], s[54:55] op_sel_hi:[1,1,0]
	v_pk_fma_f32 v[174:175], v[184:185], v[174:175], s[56:57] op_sel_hi:[1,1,0]
	v_fma_f32 v186, |v176|, s40, 1.0
	v_fma_f32 v187, |v177|, s40, 1.0
	v_pk_mul_f32 v[174:175], v[184:185], v[174:175]
	v_rcp_f32_e32 v186, v186
	v_rcp_f32_e32 v187, v187
	v_pk_mul_f32 v[174:175], v[178:179], v[174:175]
	v_max_f32_e32 v178, 0, v180
	v_max_f32_e32 v179, 0, v181
	v_fma_f32 v174, -|v180|, v174, v178
	v_fma_f32 v175, -|v181|, v175, v179
	v_pk_mul_f32 v[184:185], v[176:177], v[176:177]
	v_pk_fma_f32 v[156:157], v[186:187], s[42:43], v[156:157] op_sel_hi:[1,0,0]
	s_nop 0
	v_pk_mul_f32 v[178:179], v[184:185], s[58:59] op_sel_hi:[1,0]
	v_pk_fma_f32 v[156:157], v[186:187], v[156:157], s[52:53] op_sel_hi:[1,1,0]
	v_exp_f32_e32 v178, v178
	v_exp_f32_e32 v179, v179
	v_pk_fma_f32 v[156:157], v[186:187], v[156:157], s[54:55] op_sel_hi:[1,1,0]
	v_pk_fma_f32 v[156:157], v[186:187], v[156:157], s[56:57] op_sel_hi:[1,1,0]
	s_nop 0
	v_pk_mul_f32 v[156:157], v[186:187], v[156:157]
	s_nop 0
	v_pk_mul_f32 v[156:157], v[178:179], v[156:157]
	s_nop 0
	v_max_f32_e32 v178, 0, v176
	v_max_f32_e32 v179, 0, v177
	v_fma_f32 v156, -|v176|, v156, v178
	v_fma_f32 v157, -|v177|, v157, v179
	v_cvt_pk_bf16_f32 v176, v170, v171
	s_nop 0
	v_cvt_pk_bf16_f32 v177, v172, v173
	v_cvt_pk_bf16_f32 v178, v174, v175
	s_nop 1
	s_and_b64 vcc, exec, s[10:11]
	v_cvt_pk_bf16_f32 v179, v156, v157
	global_store_dwordx4 v[182:183], v[176:179], off offset:256
	s_cbranch_vccnz .LBB0_948
	v_mul_f32_e32 v158, v158, v158
	v_fmac_f32_e32 v158, v151, v151
	v_mul_f32_e32 v151, v165, v165
	v_fmac_f32_e32 v151, v159, v159
	v_add_f32_e32 v151, v158, v151
	v_mul_f32_e32 v158, v167, v167
	v_mul_f32_e32 v159, v169, v169
	v_fmac_f32_e32 v158, v166, v166
	v_fmac_f32_e32 v159, v168, v168
	v_add_f32_e32 v158, v158, v159
	v_add_f32_e32 v151, v151, v158
	v_mul_f32_e32 v158, v171, v171
	v_mul_f32_e32 v159, v173, v173
	v_fmac_f32_e32 v158, v170, v170
	v_fmac_f32_e32 v159, v172, v172
	v_add_f32_e32 v158, v158, v159
	v_mul_f32_e32 v159, v175, v175
	v_mul_f32_e32 v157, v157, v157
	v_fmac_f32_e32 v159, v174, v174
	v_fmac_f32_e32 v157, v156, v156
	v_add_f32_e32 v156, v159, v157
	v_add_f32_e32 v156, v158, v156
	v_and_b32_e32 v157, 64, v164
	v_add_f32_e32 v151, v151, v156
	v_xor_b32_e32 v156, 16, v164
	v_add_u32_e32 v157, 64, v157
	v_cmp_lt_i32_e32 vcc, v156, v157
	s_nop 1
	v_cndmask_b32_e32 v156, v164, v156, vcc
	v_lshlrev_b32_e32 v156, 2, v156
	ds_bpermute_b32 v156, v156, v151
	s_waitcnt lgkmcnt(0)
	v_add_f32_e32 v151, v151, v156
	v_xor_b32_e32 v156, 32, v164
	v_cmp_lt_i32_e32 vcc, v156, v157
	s_nop 1
	v_cndmask_b32_e32 v156, v164, v156, vcc
	v_lshlrev_b32_e32 v156, 2, v156
	ds_bpermute_b32 v156, v156, v151
	s_and_saveexec_b64 s[78:79], s[4:5]
	s_cbranch_execz .LBB0_947
	v_lshlrev_b64 v[154:155], 6, v[154:155]
	v_lshl_add_u64 v[154:155], s[18:19], 0, v[154:155]
	v_lshl_add_u64 v[154:155], s[76:77], 2, v[154:155]
	s_lshl_b32 s14, s59, 2
	v_lshl_add_u64 v[154:155], v[154:155], 0, s[14:15]
	s_waitcnt lgkmcnt(0)
	v_add_f32_e32 v151, v151, v156
	global_store_dword v[154:155], v151, off

; __device__ __forceinline__ float dot4(f32x4 v) { return (v[0] * v[0] + v[1] * v[1]) + (v[2] * v[2] + v[3] * v[3]); }
; __device__ __forceinline__ u32x2 pack4(f32x4 v) { u32x2 w; w.x = cvt_pk_bf16(v[0], v[1]); w.y = cvt_pk_bf16(v[2], v[3]); return w; }
; __device__ __forceinline__ f32x4 gelu4(f32x4 v) { f32x2 a = gelu_pk((f32x2){v[0], v[1]}), b = gelu_pk((f32x2){v[2], v[3]}); return (f32x4){a.x, a.y, b.x, b.y}; }
; __device__ __forceinline__ f32x2 gelu_pk(f32x2 v) {
;     const f32x2 av = __builtin_elementwise_abs(v), d = av * 0.2316418882f + 1.0f;
;     f32x2 t; t.x = __builtin_amdgcn_rcpf(d.x); t.y = __builtin_amdgcn_rcpf(d.y);
;     f32x2 q = t * 0.5307027145f + (-0.7265760135f); q = q * t + 0.7107068705f; q = q * t + (-0.142248368f); q = q * t + 0.127414796f; q = q * t;
;     const f32x2 s = (v * v) * (-0.72134752044f);
;     f32x2 e; e.x = __builtin_amdgcn_exp2f(s.x); e.y = __builtin_amdgcn_exp2f(s.y);
;     const f32x2 m = v * (q * e), r = v - m;
;     f32x2 o; o.x = v.x < 0.f ? m.x : r.x; o.y = v.y < 0.f ? m.y : r.y; return o;
; template <int EK>
; __device__ __forceinline__ void epi_tile(const f32x4 (&acc)[2][2][4][2], const Unit& u, int wr, int wc, int fr, int fq, const EpiArgs& E, const LAS float* rt) {
;     ...
;             } else if (EK == EK_GELU) {
;                 const float r = rr[ai][m]; float ss = 0.f;
; #pragma unroll
;                 for (int bj = 0; bj < 2; ++bj) { const int col = u.pn * BM + bj * HALF + wc * 32 + fq * 8;
;                     const f32x4 z0 = gelu4(acc[ai][bj][m][0] * r), z1 = gelu4(acc[ai][bj][m][1] * r); ss += dot4(z0) + dot4(z1);
;                     const u32x2 lo = pack4(z0), hi = pack4(z1);
;                     *(u32x4*)(E.ob + (size_t)row * E.ldb + col) = (u32x4){lo.x, lo.y, hi.x, hi.y}; }
.LBB0_948:
	v_pk_mul_f32 v[158:159], v[46:47], v[152:153] op_sel_hi:[1,0]
	v_pk_mul_f32 v[168:169], v[48:49], v[152:153] op_sel_hi:[1,0]
	s_waitcnt lgkmcnt(0)
	v_fma_f32 v156, |v158|, s40, 1.0
	v_fma_f32 v157, |v159|, s40, 1.0
	v_pk_mul_f32 v[172:173], v[158:159], v[158:159]
	v_rcp_f32_e32 v166, v156
	v_rcp_f32_e32 v167, v157
	v_mov_b64_e32 v[156:157], s[44:45]
	v_pk_mul_f32 v[172:173], v[172:173], s[58:59] op_sel_hi:[1,0]
	v_pk_fma_f32 v[170:171], v[166:167], s[42:43], v[156:157] op_sel_hi:[1,0,0]
	v_exp_f32_e32 v172, v172
	v_pk_fma_f32 v[170:171], v[166:167], v[170:171], s[52:53] op_sel_hi:[1,1,0]
	v_exp_f32_e32 v173, v173
	v_pk_fma_f32 v[170:171], v[166:167], v[170:171], s[54:55] op_sel_hi:[1,1,0]
	v_pk_fma_f32 v[170:171], v[166:167], v[170:171], s[56:57] op_sel_hi:[1,1,0]
	v_fma_f32 v174, |v168|, s40, 1.0
	v_fma_f32 v175, |v169|, s40, 1.0
	v_pk_mul_f32 v[166:167], v[166:167], v[170:171]
	v_rcp_f32_e32 v174, v174
	v_rcp_f32_e32 v175, v175
	v_pk_mul_f32 v[166:167], v[172:173], v[166:167]
	v_max_f32_e32 v172, 0, v158
	v_max_f32_e32 v173, 0, v159
	v_fma_f32 v151, -|v158|, v166, v172
	v_fma_f32 v158, -|v159|, v167, v173
	v_pk_mul_f32 v[170:171], v[168:169], v[168:169]
	v_pk_mul_f32 v[170:171], v[170:171], s[58:59] op_sel_hi:[1,0]
	v_add_u32_e32 v154, 0x80, v150
	v_pk_fma_f32 v[166:167], v[174:175], s[42:43], v[156:157] op_sel_hi:[1,0,0]
	v_exp_f32_e32 v170, v170
	v_pk_fma_f32 v[166:167], v[174:175], v[166:167], s[52:53] op_sel_hi:[1,1,0]
	v_exp_f32_e32 v171, v171
	v_pk_fma_f32 v[166:167], v[174:175], v[166:167], s[54:55] op_sel_hi:[1,1,0]
	v_pk_mul_f32 v[172:173], v[42:43], v[152:153] op_sel_hi:[1,0]
	v_pk_fma_f32 v[166:167], v[174:175], v[166:167], s[56:57] op_sel_hi:[1,1,0]
	v_pk_mul_f32 v[166:167], v[174:175], v[166:167]
	v_fma_f32 v174, |v172|, s40, 1.0
	v_fma_f32 v175, |v173|, s40, 1.0
	v_pk_mul_f32 v[166:167], v[170:171], v[166:167]
	v_rcp_f32_e32 v174, v174
	v_rcp_f32_e32 v175, v175
	v_max_f32_e32 v170, 0, v168
	v_max_f32_e32 v171, 0, v169
	v_fma_f32 v159, -|v168|, v166, v170
	v_fma_f32 v165, -|v169|, v167, v171
	v_ashrrev_i32_e32 v155, 31, v154
	v_pk_mul_f32 v[168:169], v[44:45], v[152:153] op_sel_hi:[1,0]
	s_nop 0
	v_pk_mul_f32 v[170:171], v[172:173], v[172:173]
	v_pk_fma_f32 v[166:167], v[174:175], s[42:43], v[156:157] op_sel_hi:[1,0,0]
	v_pk_mul_f32 v[170:171], v[170:171], s[58:59] op_sel_hi:[1,0]
	v_pk_fma_f32 v[166:167], v[174:175], v[166:167], s[52:53] op_sel_hi:[1,1,0]
	v_exp_f32_e32 v170, v170
	v_exp_f32_e32 v171, v171
	v_pk_fma_f32 v[166:167], v[174:175], v[166:167], s[54:55] op_sel_hi:[1,1,0]
	v_pk_fma_f32 v[166:167], v[174:175], v[166:167], s[56:57] op_sel_hi:[1,1,0]
	v_fma_f32 v176, |v168|, s40, 1.0
	v_fma_f32 v177, |v169|, s40, 1.0
	v_pk_mul_f32 v[166:167], v[174:175], v[166:167]
	v_rcp_f32_e32 v176, v176
	v_rcp_f32_e32 v177, v177
	v_pk_mul_f32 v[166:167], v[170:171], v[166:167]
	v_max_f32_e32 v170, 0, v172
	v_max_f32_e32 v171, 0, v173
	v_fma_f32 v166, -|v172|, v166, v170
	v_fma_f32 v167, -|v173|, v167, v171
	v_pk_mul_f32 v[174:175], v[168:169], v[168:169]
	v_pk_mul_f32 v[172:173], v[174:175], s[58:59] op_sel_hi:[1,0]
	v_lshlrev_b64 v[174:175], 12, v[154:155]
	v_pk_fma_f32 v[170:171], v[176:177], s[42:43], v[156:157] op_sel_hi:[1,0,0]
	v_exp_f32_e32 v172, v172
	v_pk_fma_f32 v[170:171], v[176:177], v[170:171], s[52:53] op_sel_hi:[1,1,0]
	v_exp_f32_e32 v173, v173
	v_pk_fma_f32 v[170:171], v[176:177], v[170:171], s[54:55] op_sel_hi:[1,1,0]
	v_pk_fma_f32 v[170:171], v[176:177], v[170:171], s[56:57] op_sel_hi:[1,1,0]
	v_lshl_add_u64 v[174:175], s[64:65], 0, v[174:175]
	v_pk_mul_f32 v[170:171], v[176:177], v[170:171]
	v_pk_mul_f32 v[176:177], v[14:15], v[152:153] op_sel_hi:[1,0]
	v_pk_mul_f32 v[170:171], v[172:173], v[170:171]
	v_fma_f32 v178, |v176|, s40, 1.0
	v_fma_f32 v179, |v177|, s40, 1.0
	v_rcp_f32_e32 v178, v178
	v_rcp_f32_e32 v179, v179
	v_max_f32_e32 v172, 0, v168
	v_max_f32_e32 v173, 0, v169
	v_fma_f32 v168, -|v168|, v170, v172
	v_fma_f32 v169, -|v169|, v171, v173
	v_lshl_add_u64 v[180:181], v[146:147], 1, v[174:175]
	v_cvt_pk_bf16_f32 v170, v151, v158
	v_pk_mul_f32 v[174:175], v[176:177], v[176:177]
	v_cvt_pk_bf16_f32 v172, v166, v167
	s_nop 0
	v_cvt_pk_bf16_f32 v171, v159, v165
	v_cvt_pk_bf16_f32 v173, v168, v169
	global_store_dwordx4 v[180:181], v[170:173], off
	v_pk_mul_f32 v[174:175], v[174:175], s[58:59] op_sel_hi:[1,0]
	v_cmp_gt_f32_e32 vcc, 0, v176
	v_pk_fma_f32 v[170:171], v[178:179], s[42:43], v[156:157] op_sel_hi:[1,0,0]
	v_pk_mul_f32 v[172:173], v[16:17], v[152:153] op_sel_hi:[1,0]
	v_pk_fma_f32 v[170:171], v[178:179], v[170:171], s[52:53] op_sel_hi:[1,1,0]
	v_exp_f32_e32 v174, v174
	v_exp_f32_e32 v175, v175
	v_pk_fma_f32 v[170:171], v[178:179], v[170:171], s[54:55] op_sel_hi:[1,1,0]
	v_pk_fma_f32 v[170:171], v[178:179], v[170:171], s[56:57] op_sel_hi:[1,1,0]
	v_fma_f32 v182, |v172|, s40, 1.0
; __device__ __forceinline__ float dot4(f32x4 v) { return (v[0] * v[0] + v[1] * v[1]) + (v[2] * v[2] + v[3] * v[3]); }
; __device__ __forceinline__ u32x2 pack4(f32x4 v) { u32x2 w; w.x = cvt_pk_bf16(v[0], v[1]); w.y = cvt_pk_bf16(v[2], v[3]); return w; }
; __device__ __forceinline__ float quad_sum(float s) { s += __shfl_xor(s, 16); s += __shfl_xor(s, 32); return s; }
; __device__ __forceinline__ f32x4 gelu4(f32x4 v) { f32x2 a = gelu_pk((f32x2){v[0], v[1]}), b = gelu_pk((f32x2){v[2], v[3]}); return (f32x4){a.x, a.y, b.x, b.y}; }
; __device__ __forceinline__ f32x2 gelu_pk(f32x2 v) {
;     const f32x2 av = __builtin_elementwise_abs(v), d = av * 0.2316418882f + 1.0f;
;     f32x2 t; t.x = __builtin_amdgcn_rcpf(d.x); t.y = __builtin_amdgcn_rcpf(d.y);
;     f32x2 q = t * 0.5307027145f + (-0.7265760135f); q = q * t + 0.7107068705f; q = q * t + (-0.142248368f); q = q * t + 0.127414796f; q = q * t;
;     const f32x2 s = (v * v) * (-0.72134752044f);
;     f32x2 e; e.x = __builtin_amdgcn_exp2f(s.x); e.y = __builtin_amdgcn_exp2f(s.y);
;     const f32x2 m = v * (q * e), r = v - m;
;     f32x2 o; o.x = v.x < 0.f ? m.x : r.x; o.y = v.y < 0.f ? m.y : r.y; return o;
; template <int EK>
; __device__ __forceinline__ void epi_tile(const f32x4 (&acc)[2][2][4][2], const Unit& u, int wr, int wc, int fr, int fq, const EpiArgs& E, const LAS float* rt) {
;     ...
;                 for (int bj = 0; bj < 2; ++bj) { const int col = u.pn * BM + bj * HALF + wc * 32 + fq * 8;
;                     const f32x4 z0 = gelu4(acc[ai][bj][m][0] * r), z1 = gelu4(acc[ai][bj][m][1] * r); ss += dot4(z0) + dot4(z1);
;                     const u32x2 lo = pack4(z0), hi = pack4(z1);
;                     *(u32x4*)(E.ob + (size_t)row * E.ldb + col) = (u32x4){lo.x, lo.y, hi.x, hi.y}; }
;                 if (u.pn >= 4) { ss = quad_sum(ss); if (fq == 0) E.stOut[(size_t)row * 16 + (u.pn - 4) * 4 + wc] = ss; }
	v_fma_f32 v183, |v173|, s40, 1.0
	v_pk_mul_f32 v[170:171], v[178:179], v[170:171]
	v_rcp_f32_e32 v182, v182
	v_rcp_f32_e32 v183, v183
	v_pk_mul_f32 v[170:171], v[174:175], v[170:171]
	v_pk_mul_f32 v[178:179], v[172:173], v[172:173]
	v_pk_mul_f32 v[174:175], v[176:177], v[170:171]
	v_pk_fma_f32 v[170:171], v[176:177], v[170:171], v[176:177] neg_lo:[1,0,0] neg_hi:[1,0,0]
	s_nop 0
	v_cndmask_b32_e32 v170, v170, v174, vcc
	v_cmp_gt_f32_e32 vcc, 0, v177
	v_pk_mul_f32 v[176:177], v[178:179], s[58:59] op_sel_hi:[1,0]
	v_pk_mul_f32 v[178:179], v[10:11], v[152:153] op_sel_hi:[1,0]
	v_cndmask_b32_e32 v171, v171, v175, vcc
	v_pk_fma_f32 v[174:175], v[182:183], s[42:43], v[156:157] op_sel_hi:[1,0,0]
	v_exp_f32_e32 v176, v176
	v_pk_fma_f32 v[174:175], v[182:183], v[174:175], s[52:53] op_sel_hi:[1,1,0]
	v_exp_f32_e32 v177, v177
	v_pk_fma_f32 v[174:175], v[182:183], v[174:175], s[54:55] op_sel_hi:[1,1,0]
	v_pk_fma_f32 v[174:175], v[182:183], v[174:175], s[56:57] op_sel_hi:[1,1,0]
	v_pk_mul_f32 v[184:185], v[178:179], v[178:179]
	v_pk_mul_f32 v[174:175], v[182:183], v[174:175]
	v_fma_f32 v182, |v178|, s40, 1.0
	v_fma_f32 v183, |v179|, s40, 1.0
	v_pk_mul_f32 v[174:175], v[176:177], v[174:175]
	v_rcp_f32_e32 v182, v182
	v_rcp_f32_e32 v183, v183
	v_max_f32_e32 v176, 0, v172
	v_max_f32_e32 v177, 0, v173
	v_fma_f32 v172, -|v172|, v174, v176
	v_fma_f32 v173, -|v173|, v175, v177
	v_pk_mul_f32 v[184:185], v[184:185], s[58:59] op_sel_hi:[1,0]
	v_exp_f32_e32 v184, v184
	v_exp_f32_e32 v185, v185
	v_pk_mul_f32 v[176:177], v[12:13], v[152:153] op_sel_hi:[1,0]
	v_pk_fma_f32 v[174:175], v[182:183], s[42:43], v[156:157] op_sel_hi:[1,0,0]
	v_pk_fma_f32 v[174:175], v[182:183], v[174:175], s[52:53] op_sel_hi:[1,1,0]
	v_pk_fma_f32 v[174:175], v[182:183], v[174:175], s[54:55] op_sel_hi:[1,1,0]
	v_fma_f32 v186, |v176|, s40, 1.0
	v_fma_f32 v187, |v177|, s40, 1.0
	v_pk_fma_f32 v[174:175], v[182:183], v[174:175], s[56:57] op_sel_hi:[1,1,0]
	v_rcp_f32_e32 v186, v186
	v_rcp_f32_e32 v187, v187
	v_pk_mul_f32 v[174:175], v[182:183], v[174:175]
	v_pk_mul_f32 v[182:183], v[176:177], v[176:177]
	v_pk_mul_f32 v[174:175], v[184:185], v[174:175]
	v_max_f32_e32 v184, 0, v178
	v_max_f32_e32 v185, 0, v179
	v_fma_f32 v152, -|v178|, v174, v184
	v_fma_f32 v174, -|v179|, v175, v185
	v_pk_fma_f32 v[156:157], v[186:187], s[42:43], v[156:157] op_sel_hi:[1,0,0]
	v_pk_mul_f32 v[178:179], v[182:183], s[58:59] op_sel_hi:[1,0]
	v_pk_fma_f32 v[156:157], v[186:187], v[156:157], s[52:53] op_sel_hi:[1,1,0]
	v_exp_f32_e32 v178, v178
	v_exp_f32_e32 v179, v179
	v_pk_fma_f32 v[156:157], v[186:187], v[156:157], s[54:55] op_sel_hi:[1,1,0]
	v_pk_fma_f32 v[156:157], v[186:187], v[156:157], s[56:57] op_sel_hi:[1,1,0]
	v_pk_mul_f32 v[156:157], v[186:187], v[156:157]
	s_nop 0
	v_pk_mul_f32 v[156:157], v[178:179], v[156:157]
	s_nop 0
	v_max_f32_e32 v178, 0, v176
	v_max_f32_e32 v179, 0, v177
	v_fma_f32 v156, -|v176|, v156, v178
	v_fma_f32 v157, -|v177|, v157, v179
	v_cvt_pk_bf16_f32 v176, v170, v171
	s_nop 0
	v_cvt_pk_bf16_f32 v177, v172, v173
	v_cvt_pk_bf16_f32 v178, v152, v174
	s_nop 1
	s_and_b64 vcc, exec, s[10:11]
	v_cvt_pk_bf16_f32 v179, v156, v157
	global_store_dwordx4 v[180:181], v[176:179], off offset:256
	s_cbranch_vccnz .LBB0_952
	v_mul_f32_e32 v158, v158, v158
	v_fmac_f32_e32 v158, v151, v151
	v_mul_f32_e32 v151, v165, v165
	v_fmac_f32_e32 v151, v159, v159
	v_add_f32_e32 v151, v158, v151
	v_mul_f32_e32 v158, v167, v167
	v_mul_f32_e32 v159, v169, v169
	v_fmac_f32_e32 v158, v166, v166
	v_fmac_f32_e32 v159, v168, v168
	v_add_f32_e32 v158, v158, v159
	v_add_f32_e32 v151, v151, v158
	v_mul_f32_e32 v158, v171, v171
	v_mul_f32_e32 v159, v173, v173
	v_fmac_f32_e32 v158, v170, v170
	v_fmac_f32_e32 v159, v172, v172
	v_add_f32_e32 v158, v158, v159
	v_mul_f32_e32 v159, v174, v174
	v_fmac_f32_e32 v159, v152, v152
	v_mul_f32_e32 v152, v157, v157
	v_fmac_f32_e32 v152, v156, v156
	v_add_f32_e32 v152, v159, v152
	v_add_f32_e32 v152, v158, v152
	v_and_b32_e32 v156, 64, v164
	v_add_f32_e32 v151, v151, v152
	v_xor_b32_e32 v152, 16, v164
	v_add_u32_e32 v156, 64, v156
	v_cmp_lt_i32_e32 vcc, v152, v156
	s_nop 1
	v_cndmask_b32_e32 v152, v164, v152, vcc
	v_lshlrev_b32_e32 v152, 2, v152
	ds_bpermute_b32 v152, v152, v151
	s_waitcnt lgkmcnt(0)
	v_add_f32_e32 v151, v151, v152
	v_xor_b32_e32 v152, 32, v164
	v_cmp_lt_i32_e32 vcc, v152, v156
	s_nop 1
	v_cndmask_b32_e32 v152, v164, v152, vcc
	v_lshlrev_b32_e32 v152, 2, v152
	ds_bpermute_b32 v152, v152, v151
	s_and_saveexec_b64 s[78:79], s[4:5]
	s_cbranch_execz .LBB0_951
	v_lshlrev_b64 v[154:155], 6, v[154:155]
	v_lshl_add_u64 v[154:155], s[18:19], 0, v[154:155]
	v_lshl_add_u64 v[154:155], s[76:77], 2, v[154:155]
	s_lshl_b32 s14, s59, 2
	v_lshl_add_u64 v[154:155], v[154:155], 0, s[14:15]
	s_waitcnt lgkmcnt(0)
	v_add_f32_e32 v151, v151, v152
	global_store_dword v[154:155], v151, off

; __device__ __forceinline__ float dot4(f32x4 v) { return (v[0] * v[0] + v[1] * v[1]) + (v[2] * v[2] + v[3] * v[3]); }
; __device__ __forceinline__ u32x2 pack4(f32x4 v) { u32x2 w; w.x = cvt_pk_bf16(v[0], v[1]); w.y = cvt_pk_bf16(v[2], v[3]); return w; }
; __device__ __forceinline__ f32x4 gelu4(f32x4 v) { f32x2 a = gelu_pk((f32x2){v[0], v[1]}), b = gelu_pk((f32x2){v[2], v[3]}); return (f32x4){a.x, a.y, b.x, b.y}; }
; __device__ __forceinline__ f32x2 gelu_pk(f32x2 v) {
;     const f32x2 av = __builtin_elementwise_abs(v), d = av * 0.2316418882f + 1.0f;
;     f32x2 t; t.x = __builtin_amdgcn_rcpf(d.x); t.y = __builtin_amdgcn_rcpf(d.y);
;     f32x2 q = t * 0.5307027145f + (-0.7265760135f); q = q * t + 0.7107068705f; q = q * t + (-0.142248368f); q = q * t + 0.127414796f; q = q * t;
;     const f32x2 s = (v * v) * (-0.72134752044f);
;     f32x2 e; e.x = __builtin_amdgcn_exp2f(s.x); e.y = __builtin_amdgcn_exp2f(s.y);
;     const f32x2 m = v * (q * e), r = v - m;
;     f32x2 o; o.x = v.x < 0.f ? m.x : r.x; o.y = v.y < 0.f ? m.y : r.y; return o;
; template <int EK>
; __device__ __forceinline__ void epi_tile(const f32x4 (&acc)[2][2][4][2], const Unit& u, int wr, int wc, int fr, int fq, const EpiArgs& E, const LAS float* rt) {
;     ...
;             } else if (EK == EK_GELU) {
;                 const float r = rr[ai][m]; float ss = 0.f;
; #pragma unroll
;                 for (int bj = 0; bj < 2; ++bj) { const int col = u.pn * BM + bj * HALF + wc * 32 + fq * 8;
;                     const f32x4 z0 = gelu4(acc[ai][bj][m][0] * r), z1 = gelu4(acc[ai][bj][m][1] * r); ss += dot4(z0) + dot4(z1);
;                     const u32x2 lo = pack4(z0), hi = pack4(z1);
;                     *(u32x4*)(E.ob + (size_t)row * E.ldb + col) = (u32x4){lo.x, lo.y, hi.x, hi.y}; }
.LBB0_952:
	v_mov_b32_e32 v172, v153
	v_pk_mul_f32 v[156:157], v[38:39], v[172:173] op_sel_hi:[1,0]
	v_pk_mul_f32 v[166:167], v[40:41], v[172:173] op_sel_hi:[1,0]
	v_fma_f32 v154, |v156|, s40, 1.0
	v_fma_f32 v155, |v157|, s40, 1.0
	v_pk_mul_f32 v[170:171], v[156:157], v[156:157]
	v_rcp_f32_e32 v158, v154
	v_rcp_f32_e32 v159, v155
	v_mov_b64_e32 v[154:155], s[44:45]
	v_pk_mul_f32 v[170:171], v[170:171], s[58:59] op_sel_hi:[1,0]
	v_pk_fma_f32 v[168:169], v[158:159], s[42:43], v[154:155] op_sel_hi:[1,0,0]
	v_exp_f32_e32 v170, v170
	v_pk_fma_f32 v[168:169], v[158:159], v[168:169], s[52:53] op_sel_hi:[1,1,0]
	v_exp_f32_e32 v171, v171
	v_pk_fma_f32 v[168:169], v[158:159], v[168:169], s[54:55] op_sel_hi:[1,1,0]
	v_pk_fma_f32 v[168:169], v[158:159], v[168:169], s[56:57] op_sel_hi:[1,1,0]
	v_fma_f32 v174, |v166|, s40, 1.0
	v_fma_f32 v175, |v167|, s40, 1.0
	v_pk_mul_f32 v[158:159], v[158:159], v[168:169]
	v_rcp_f32_e32 v174, v174
	v_rcp_f32_e32 v175, v175
	v_pk_mul_f32 v[158:159], v[170:171], v[158:159]
	v_max_f32_e32 v170, 0, v156
	v_max_f32_e32 v171, 0, v157
	v_fma_f32 v151, -|v156|, v158, v170
	v_fma_f32 v156, -|v157|, v159, v171
	v_pk_mul_f32 v[168:169], v[166:167], v[166:167]
	v_pk_mul_f32 v[168:169], v[168:169], s[58:59] op_sel_hi:[1,0]
	s_waitcnt lgkmcnt(0)
	v_add_u32_e32 v152, 0x90, v150
	v_pk_fma_f32 v[158:159], v[174:175], s[42:43], v[154:155] op_sel_hi:[1,0,0]
	v_exp_f32_e32 v168, v168
	v_pk_fma_f32 v[158:159], v[174:175], v[158:159], s[52:53] op_sel_hi:[1,1,0]
	v_exp_f32_e32 v169, v169
	v_pk_fma_f32 v[158:159], v[174:175], v[158:159], s[54:55] op_sel_hi:[1,1,0]
	v_pk_mul_f32 v[170:171], v[34:35], v[172:173] op_sel_hi:[1,0]
	v_pk_fma_f32 v[158:159], v[174:175], v[158:159], s[56:57] op_sel_hi:[1,1,0]
	v_pk_mul_f32 v[158:159], v[174:175], v[158:159]
	v_fma_f32 v174, |v170|, s40, 1.0
	v_fma_f32 v175, |v171|, s40, 1.0
	v_pk_mul_f32 v[158:159], v[168:169], v[158:159]
	v_rcp_f32_e32 v174, v174
	v_rcp_f32_e32 v175, v175
	v_max_f32_e32 v168, 0, v166
	v_max_f32_e32 v169, 0, v167
	v_fma_f32 v157, -|v166|, v158, v168
	v_fma_f32 v158, -|v167|, v159, v169
	v_pk_mul_f32 v[176:177], v[170:171], v[170:171]
	v_pk_mul_f32 v[176:177], v[176:177], s[58:59] op_sel_hi:[1,0]
	v_pk_mul_f32 v[166:167], v[36:37], v[172:173] op_sel_hi:[1,0]
	v_pk_fma_f32 v[168:169], v[174:175], s[42:43], v[154:155] op_sel_hi:[1,0,0]
	v_exp_f32_e32 v176, v176
	v_pk_fma_f32 v[168:169], v[174:175], v[168:169], s[52:53] op_sel_hi:[1,1,0]
	v_exp_f32_e32 v177, v177
	v_pk_fma_f32 v[168:169], v[174:175], v[168:169], s[54:55] op_sel_hi:[1,1,0]
	v_pk_fma_f32 v[168:169], v[174:175], v[168:169], s[56:57] op_sel_hi:[1,1,0]
	v_fma_f32 v178, |v166|, s40, 1.0
	v_fma_f32 v179, |v167|, s40, 1.0
	v_pk_mul_f32 v[168:169], v[174:175], v[168:169]
	v_rcp_f32_e32 v178, v178
	v_rcp_f32_e32 v179, v179
	v_pk_mul_f32 v[168:169], v[176:177], v[168:169]
	v_max_f32_e32 v176, 0, v170
	v_max_f32_e32 v177, 0, v171
	v_fma_f32 v159, -|v170|, v168, v176
	v_fma_f32 v165, -|v171|, v169, v177
	v_pk_mul_f32 v[174:175], v[166:167], v[166:167]
	v_pk_mul_f32 v[170:171], v[174:175], s[58:59] op_sel_hi:[1,0]
	v_ashrrev_i32_e32 v153, 31, v152
	v_pk_fma_f32 v[168:169], v[178:179], s[42:43], v[154:155] op_sel_hi:[1,0,0]
	v_exp_f32_e32 v170, v170
	v_pk_fma_f32 v[168:169], v[178:179], v[168:169], s[52:53] op_sel_hi:[1,1,0]
	v_exp_f32_e32 v171, v171
	v_pk_fma_f32 v[168:169], v[178:179], v[168:169], s[54:55] op_sel_hi:[1,1,0]
	v_pk_mul_f32 v[176:177], v[6:7], v[172:173] op_sel_hi:[1,0]
	v_pk_fma_f32 v[168:169], v[178:179], v[168:169], s[56:57] op_sel_hi:[1,1,0]
	v_pk_mul_f32 v[168:169], v[178:179], v[168:169]
	v_fma_f32 v178, |v176|, s40, 1.0
	v_fma_f32 v179, |v177|, s40, 1.0
	v_pk_mul_f32 v[168:169], v[170:171], v[168:169]
	v_rcp_f32_e32 v178, v178
	v_rcp_f32_e32 v179, v179
	v_max_f32_e32 v170, 0, v166
	v_max_f32_e32 v171, 0, v167
	v_fma_f32 v166, -|v166|, v168, v170
	v_fma_f32 v167, -|v167|, v169, v171
	v_lshlrev_b64 v[174:175], 12, v[152:153]
	v_lshl_add_u64 v[174:175], s[64:65], 0, v[174:175]
	v_cvt_pk_bf16_f32 v168, v151, v156
	v_lshl_add_u64 v[180:181], v[146:147], 1, v[174:175]
	v_cvt_pk_bf16_f32 v169, v157, v158
	v_pk_mul_f32 v[174:175], v[176:177], v[176:177]
	v_cvt_pk_bf16_f32 v170, v159, v165
	v_cvt_pk_bf16_f32 v171, v166, v167
	global_store_dwordx4 v[180:181], v[168:171], off
	v_pk_mul_f32 v[174:175], v[174:175], s[58:59] op_sel_hi:[1,0]
	v_cmp_gt_f32_e32 vcc, 0, v176
	v_pk_fma_f32 v[168:169], v[178:179], s[42:43], v[154:155] op_sel_hi:[1,0,0]
	v_pk_mul_f32 v[170:171], v[8:9], v[172:173] op_sel_hi:[1,0]
	v_pk_fma_f32 v[168:169], v[178:179], v[168:169], s[52:53] op_sel_hi:[1,1,0]
	v_exp_f32_e32 v174, v174
	v_exp_f32_e32 v175, v175
	v_pk_fma_f32 v[168:169], v[178:179], v[168:169], s[54:55] op_sel_hi:[1,1,0]
	v_pk_fma_f32 v[168:169], v[178:179], v[168:169], s[56:57] op_sel_hi:[1,1,0]
	v_fma_f32 v182, |v170|, s40, 1.0
	v_fma_f32 v183, |v171|, s40, 1.0
; __device__ __forceinline__ float dot4(f32x4 v) { return (v[0] * v[0] + v[1] * v[1]) + (v[2] * v[2] + v[3] * v[3]); }
; __device__ __forceinline__ u32x2 pack4(f32x4 v) { u32x2 w; w.x = cvt_pk_bf16(v[0], v[1]); w.y = cvt_pk_bf16(v[2], v[3]); return w; }
; __device__ __forceinline__ float quad_sum(float s) { s += __shfl_xor(s, 16); s += __shfl_xor(s, 32); return s; }
; __device__ __forceinline__ f32x4 gelu4(f32x4 v) { f32x2 a = gelu_pk((f32x2){v[0], v[1]}), b = gelu_pk((f32x2){v[2], v[3]}); return (f32x4){a.x, a.y, b.x, b.y}; }
; __device__ __forceinline__ f32x2 gelu_pk(f32x2 v) {
;     const f32x2 av = __builtin_elementwise_abs(v), d = av * 0.2316418882f + 1.0f;
;     f32x2 t; t.x = __builtin_amdgcn_rcpf(d.x); t.y = __builtin_amdgcn_rcpf(d.y);
;     f32x2 q = t * 0.5307027145f + (-0.7265760135f); q = q * t + 0.7107068705f; q = q * t + (-0.142248368f); q = q * t + 0.127414796f; q = q * t;
;     const f32x2 s = (v * v) * (-0.72134752044f);
;     f32x2 e; e.x = __builtin_amdgcn_exp2f(s.x); e.y = __builtin_amdgcn_exp2f(s.y);
;     const f32x2 m = v * (q * e), r = v - m;
;     f32x2 o; o.x = v.x < 0.f ? m.x : r.x; o.y = v.y < 0.f ? m.y : r.y; return o;
; template <int EK>
; __device__ __forceinline__ void epi_tile(const f32x4 (&acc)[2][2][4][2], const Unit& u, int wr, int wc, int fr, int fq, const EpiArgs& E, const LAS float* rt) {
;     ...
;                 for (int bj = 0; bj < 2; ++bj) { const int col = u.pn * BM + bj * HALF + wc * 32 + fq * 8;
;                     const f32x4 z0 = gelu4(acc[ai][bj][m][0] * r), z1 = gelu4(acc[ai][bj][m][1] * r); ss += dot4(z0) + dot4(z1);
;                     const u32x2 lo = pack4(z0), hi = pack4(z1);
;                     *(u32x4*)(E.ob + (size_t)row * E.ldb + col) = (u32x4){lo.x, lo.y, hi.x, hi.y}; }
;                 if (u.pn >= 4) { ss = quad_sum(ss); if (fq == 0) E.stOut[(size_t)row * 16 + (u.pn - 4) * 4 + wc] = ss; }
	v_pk_mul_f32 v[168:169], v[178:179], v[168:169]
	v_rcp_f32_e32 v182, v182
	v_rcp_f32_e32 v183, v183
	v_pk_mul_f32 v[168:169], v[174:175], v[168:169]
	v_pk_mul_f32 v[178:179], v[170:171], v[170:171]
	v_pk_mul_f32 v[174:175], v[176:177], v[168:169]
	v_pk_fma_f32 v[168:169], v[176:177], v[168:169], v[176:177] neg_lo:[1,0,0] neg_hi:[1,0,0]
	s_nop 0
	v_cndmask_b32_e32 v168, v168, v174, vcc
	v_cmp_gt_f32_e32 vcc, 0, v177
	v_pk_mul_f32 v[176:177], v[178:179], s[58:59] op_sel_hi:[1,0]
	v_pk_mul_f32 v[178:179], v[2:3], v[172:173] op_sel_hi:[1,0]
	v_cndmask_b32_e32 v169, v169, v175, vcc
	v_pk_fma_f32 v[174:175], v[182:183], s[42:43], v[154:155] op_sel_hi:[1,0,0]
	v_exp_f32_e32 v176, v176
	v_pk_fma_f32 v[174:175], v[182:183], v[174:175], s[52:53] op_sel_hi:[1,1,0]
	v_exp_f32_e32 v177, v177
	v_pk_fma_f32 v[174:175], v[182:183], v[174:175], s[54:55] op_sel_hi:[1,1,0]
	v_pk_fma_f32 v[174:175], v[182:183], v[174:175], s[56:57] op_sel_hi:[1,1,0]
	s_nop 0
	v_pk_mul_f32 v[174:175], v[182:183], v[174:175]
	v_fma_f32 v182, |v178|, s40, 1.0
	v_fma_f32 v183, |v179|, s40, 1.0
	v_pk_mul_f32 v[174:175], v[176:177], v[174:175]
	v_rcp_f32_e32 v182, v182
	v_rcp_f32_e32 v183, v183
	v_max_f32_e32 v176, 0, v170
	v_max_f32_e32 v177, 0, v171
	v_fma_f32 v170, -|v170|, v174, v176
	v_fma_f32 v171, -|v171|, v175, v177
	s_nop 0
	s_nop 1
	v_pk_mul_f32 v[176:177], v[178:179], v[178:179]
	v_pk_mul_f32 v[174:175], v[4:5], v[172:173] op_sel_hi:[1,0]
	v_pk_fma_f32 v[172:173], v[182:183], s[42:43], v[154:155] op_sel_hi:[1,0,0]
	v_pk_mul_f32 v[176:177], v[176:177], s[58:59] op_sel_hi:[1,0]
	v_pk_fma_f32 v[172:173], v[182:183], v[172:173], s[52:53] op_sel_hi:[1,1,0]
	v_exp_f32_e32 v176, v176
	v_exp_f32_e32 v177, v177
	v_pk_fma_f32 v[172:173], v[182:183], v[172:173], s[54:55] op_sel_hi:[1,1,0]
	v_pk_fma_f32 v[172:173], v[182:183], v[172:173], s[56:57] op_sel_hi:[1,1,0]
	v_fma_f32 v184, |v174|, s40, 1.0
	v_fma_f32 v185, |v175|, s40, 1.0
	v_pk_mul_f32 v[172:173], v[182:183], v[172:173]
	v_rcp_f32_e32 v184, v184
	v_rcp_f32_e32 v185, v185
	v_pk_mul_f32 v[172:173], v[176:177], v[172:173]
	v_max_f32_e32 v176, 0, v178
	v_max_f32_e32 v177, 0, v179
	v_fma_f32 v172, -|v178|, v172, v176
	v_fma_f32 v173, -|v179|, v173, v177
	v_pk_mul_f32 v[182:183], v[174:175], v[174:175]
	v_pk_fma_f32 v[154:155], v[184:185], s[42:43], v[154:155] op_sel_hi:[1,0,0]
	s_nop 0
	v_pk_mul_f32 v[176:177], v[182:183], s[58:59] op_sel_hi:[1,0]
	v_pk_fma_f32 v[154:155], v[184:185], v[154:155], s[52:53] op_sel_hi:[1,1,0]
	v_exp_f32_e32 v176, v176
	v_exp_f32_e32 v177, v177
	v_pk_fma_f32 v[154:155], v[184:185], v[154:155], s[54:55] op_sel_hi:[1,1,0]
	v_pk_fma_f32 v[154:155], v[184:185], v[154:155], s[56:57] op_sel_hi:[1,1,0]
	s_nop 0
	v_pk_mul_f32 v[154:155], v[184:185], v[154:155]
	s_nop 0
	v_pk_mul_f32 v[154:155], v[176:177], v[154:155]
	s_nop 0
	v_max_f32_e32 v176, 0, v174
	v_max_f32_e32 v177, 0, v175
	v_fma_f32 v154, -|v174|, v154, v176
	v_fma_f32 v155, -|v175|, v155, v177
	v_cvt_pk_bf16_f32 v174, v168, v169
	s_nop 0
	v_cvt_pk_bf16_f32 v175, v170, v171
	v_cvt_pk_bf16_f32 v176, v172, v173
	s_nop 1
	s_and_b64 vcc, exec, s[10:11]
	v_cvt_pk_bf16_f32 v177, v154, v155
	global_store_dwordx4 v[180:181], v[174:177], off offset:256
	s_cbranch_vccnz .LBB0_956
	v_mul_f32_e32 v156, v156, v156
	v_fmac_f32_e32 v156, v151, v151
	v_mul_f32_e32 v151, v158, v158
	v_fmac_f32_e32 v151, v157, v157
	v_add_f32_e32 v151, v156, v151
	v_mul_f32_e32 v156, v165, v165
	v_mul_f32_e32 v157, v167, v167
	v_fmac_f32_e32 v156, v159, v159
	v_fmac_f32_e32 v157, v166, v166
	v_add_f32_e32 v156, v156, v157
	v_add_f32_e32 v151, v151, v156
	v_mul_f32_e32 v156, v169, v169
	v_mul_f32_e32 v157, v171, v171
	v_fmac_f32_e32 v156, v168, v168
	v_fmac_f32_e32 v157, v170, v170
	v_add_f32_e32 v156, v156, v157
	v_mul_f32_e32 v157, v173, v173
	v_mul_f32_e32 v155, v155, v155
	v_fmac_f32_e32 v157, v172, v172
	v_fmac_f32_e32 v155, v154, v154
	v_add_f32_e32 v154, v157, v155
	v_add_f32_e32 v154, v156, v154
	v_and_b32_e32 v155, 64, v164
	v_add_f32_e32 v151, v151, v154
	v_xor_b32_e32 v154, 16, v164
	v_add_u32_e32 v155, 64, v155
	v_cmp_lt_i32_e32 vcc, v154, v155
	s_nop 1
	v_cndmask_b32_e32 v154, v164, v154, vcc
	v_lshlrev_b32_e32 v154, 2, v154
	ds_bpermute_b32 v154, v154, v151
	s_waitcnt lgkmcnt(0)
	v_add_f32_e32 v151, v151, v154
	v_xor_b32_e32 v154, 32, v164
	v_cmp_lt_i32_e32 vcc, v154, v155
	s_nop 1
	v_cndmask_b32_e32 v154, v164, v154, vcc
	v_lshlrev_b32_e32 v154, 2, v154
	ds_bpermute_b32 v154, v154, v151
	s_and_saveexec_b64 s[78:79], s[4:5]
	s_cbranch_execz .LBB0_955
	v_lshlrev_b64 v[152:153], 6, v[152:153]
	v_lshl_add_u64 v[152:153], s[18:19], 0, v[152:153]
	v_lshl_add_u64 v[152:153], s[76:77], 2, v[152:153]
	s_lshl_b32 s14, s59, 2
	v_lshl_add_u64 v[152:153], v[152:153], 0, s[14:15]
	s_waitcnt lgkmcnt(0)
	v_add_f32_e32 v151, v151, v154
	global_store_dword v[152:153], v151, off

; __device__ __forceinline__ float dot4(f32x4 v) { return (v[0] * v[0] + v[1] * v[1]) + (v[2] * v[2] + v[3] * v[3]); }
; __device__ __forceinline__ u32x2 pack4(f32x4 v) { u32x2 w; w.x = cvt_pk_bf16(v[0], v[1]); w.y = cvt_pk_bf16(v[2], v[3]); return w; }
; __device__ __forceinline__ f32x4 gelu4(f32x4 v) { f32x2 a = gelu_pk((f32x2){v[0], v[1]}), b = gelu_pk((f32x2){v[2], v[3]}); return (f32x4){a.x, a.y, b.x, b.y}; }
; __device__ __forceinline__ f32x2 gelu_pk(f32x2 v) {
;     const f32x2 av = __builtin_elementwise_abs(v), d = av * 0.2316418882f + 1.0f;
;     f32x2 t; t.x = __builtin_amdgcn_rcpf(d.x); t.y = __builtin_amdgcn_rcpf(d.y);
;     f32x2 q = t * 0.5307027145f + (-0.7265760135f); q = q * t + 0.7107068705f; q = q * t + (-0.142248368f); q = q * t + 0.127414796f; q = q * t;
;     const f32x2 s = (v * v) * (-0.72134752044f);
;     f32x2 e; e.x = __builtin_amdgcn_exp2f(s.x); e.y = __builtin_amdgcn_exp2f(s.y);
;     const f32x2 m = v * (q * e), r = v - m;
;     f32x2 o; o.x = v.x < 0.f ? m.x : r.x; o.y = v.y < 0.f ? m.y : r.y; return o;
; template <int EK>
; __device__ __forceinline__ void epi_tile(const f32x4 (&acc)[2][2][4][2], const Unit& u, int wr, int wc, int fr, int fq, const EpiArgs& E, const LAS float* rt) {
;     ...
;             } else if (EK == EK_GELU) {
;                 const float r = rr[ai][m]; float ss = 0.f;
; #pragma unroll
;                 for (int bj = 0; bj < 2; ++bj) { const int col = u.pn * BM + bj * HALF + wc * 32 + fq * 8;
;                     const f32x4 z0 = gelu4(acc[ai][bj][m][0] * r), z1 = gelu4(acc[ai][bj][m][1] * r); ss += dot4(z0) + dot4(z1);
;                     const u32x2 lo = pack4(z0), hi = pack4(z1);
;                     *(u32x4*)(E.ob + (size_t)row * E.ldb + col) = (u32x4){lo.x, lo.y, hi.x, hi.y}; }
.LBB0_956:
	v_pk_mul_f32 v[156:157], v[30:31], v[148:149] op_sel_hi:[1,0]
	v_pk_mul_f32 v[166:167], v[32:33], v[148:149] op_sel_hi:[1,0]
	s_waitcnt lgkmcnt(0)
	v_fma_f32 v154, |v156|, s40, 1.0
	v_fma_f32 v155, |v157|, s40, 1.0
	v_pk_mul_f32 v[170:171], v[156:157], v[156:157]
	v_rcp_f32_e32 v158, v154
	v_rcp_f32_e32 v159, v155
	v_mov_b64_e32 v[154:155], s[44:45]
	v_pk_mul_f32 v[170:171], v[170:171], s[58:59] op_sel_hi:[1,0]
	v_pk_fma_f32 v[168:169], v[158:159], s[42:43], v[154:155] op_sel_hi:[1,0,0]
	v_exp_f32_e32 v170, v170
	v_pk_fma_f32 v[168:169], v[158:159], v[168:169], s[52:53] op_sel_hi:[1,1,0]
	v_exp_f32_e32 v171, v171
	v_pk_fma_f32 v[168:169], v[158:159], v[168:169], s[54:55] op_sel_hi:[1,1,0]
	v_pk_fma_f32 v[168:169], v[158:159], v[168:169], s[56:57] op_sel_hi:[1,1,0]
	v_fma_f32 v172, |v166|, s40, 1.0
	v_fma_f32 v173, |v167|, s40, 1.0
	v_pk_mul_f32 v[158:159], v[158:159], v[168:169]
	v_rcp_f32_e32 v172, v172
	v_rcp_f32_e32 v173, v173
	v_pk_mul_f32 v[158:159], v[170:171], v[158:159]
	v_max_f32_e32 v170, 0, v156
	v_max_f32_e32 v171, 0, v157
	v_fma_f32 v151, -|v156|, v158, v170
	v_fma_f32 v156, -|v157|, v159, v171
	v_pk_mul_f32 v[168:169], v[166:167], v[166:167]
	v_pk_mul_f32 v[168:169], v[168:169], s[58:59] op_sel_hi:[1,0]
	v_add_u32_e32 v152, 0xa0, v150
	v_pk_fma_f32 v[158:159], v[172:173], s[42:43], v[154:155] op_sel_hi:[1,0,0]
	v_exp_f32_e32 v168, v168
	v_pk_fma_f32 v[158:159], v[172:173], v[158:159], s[52:53] op_sel_hi:[1,1,0]
	v_exp_f32_e32 v169, v169
	v_pk_fma_f32 v[158:159], v[172:173], v[158:159], s[54:55] op_sel_hi:[1,1,0]
	v_pk_mul_f32 v[170:171], v[26:27], v[148:149] op_sel_hi:[1,0]
	v_pk_fma_f32 v[158:159], v[172:173], v[158:159], s[56:57] op_sel_hi:[1,1,0]
	v_pk_mul_f32 v[158:159], v[172:173], v[158:159]
	v_fma_f32 v172, |v170|, s40, 1.0
	v_fma_f32 v173, |v171|, s40, 1.0
	v_pk_mul_f32 v[158:159], v[168:169], v[158:159]
	v_rcp_f32_e32 v172, v172
	v_rcp_f32_e32 v173, v173
	v_max_f32_e32 v168, 0, v166
	v_max_f32_e32 v169, 0, v167
	v_fma_f32 v157, -|v166|, v158, v168
	v_fma_f32 v158, -|v167|, v159, v169
	v_pk_mul_f32 v[174:175], v[170:171], v[170:171]
	v_pk_mul_f32 v[174:175], v[174:175], s[58:59] op_sel_hi:[1,0]
	v_pk_mul_f32 v[166:167], v[28:29], v[148:149] op_sel_hi:[1,0]
	v_pk_fma_f32 v[168:169], v[172:173], s[42:43], v[154:155] op_sel_hi:[1,0,0]
	v_exp_f32_e32 v174, v174
	v_pk_fma_f32 v[168:169], v[172:173], v[168:169], s[52:53] op_sel_hi:[1,1,0]
	v_exp_f32_e32 v175, v175
	v_pk_fma_f32 v[168:169], v[172:173], v[168:169], s[54:55] op_sel_hi:[1,1,0]
	v_pk_fma_f32 v[168:169], v[172:173], v[168:169], s[56:57] op_sel_hi:[1,1,0]
	v_fma_f32 v176, |v166|, s40, 1.0
	v_fma_f32 v177, |v167|, s40, 1.0
	v_pk_mul_f32 v[168:169], v[172:173], v[168:169]
	v_rcp_f32_e32 v176, v176
	v_rcp_f32_e32 v177, v177
	v_pk_mul_f32 v[168:169], v[174:175], v[168:169]
	v_max_f32_e32 v174, 0, v170
	v_max_f32_e32 v175, 0, v171
	v_fma_f32 v159, -|v170|, v168, v174
	v_fma_f32 v165, -|v171|, v169, v175
	v_pk_mul_f32 v[172:173], v[166:167], v[166:167]
	v_pk_mul_f32 v[170:171], v[172:173], s[58:59] op_sel_hi:[1,0]
	v_ashrrev_i32_e32 v153, 31, v152
	v_pk_fma_f32 v[168:169], v[176:177], s[42:43], v[154:155] op_sel_hi:[1,0,0]
	v_exp_f32_e32 v170, v170
	v_pk_fma_f32 v[168:169], v[176:177], v[168:169], s[52:53] op_sel_hi:[1,1,0]
	v_exp_f32_e32 v171, v171
	v_pk_fma_f32 v[168:169], v[176:177], v[168:169], s[54:55] op_sel_hi:[1,1,0]
	v_pk_mul_f32 v[174:175], v[114:115], v[148:149] op_sel_hi:[1,0]
	v_pk_fma_f32 v[168:169], v[176:177], v[168:169], s[56:57] op_sel_hi:[1,1,0]
	v_pk_mul_f32 v[168:169], v[176:177], v[168:169]
	v_fma_f32 v176, |v174|, s40, 1.0
	v_fma_f32 v177, |v175|, s40, 1.0
	v_pk_mul_f32 v[168:169], v[170:171], v[168:169]
	v_rcp_f32_e32 v176, v176
	v_rcp_f32_e32 v177, v177
	v_max_f32_e32 v170, 0, v166
	v_max_f32_e32 v171, 0, v167
	v_fma_f32 v166, -|v166|, v168, v170
	v_fma_f32 v167, -|v167|, v169, v171
	v_lshlrev_b64 v[172:173], 12, v[152:153]
	v_lshl_add_u64 v[172:173], s[64:65], 0, v[172:173]
	v_cvt_pk_bf16_f32 v168, v151, v156
	v_lshl_add_u64 v[178:179], v[146:147], 1, v[172:173]
	v_cvt_pk_bf16_f32 v169, v157, v158
	v_pk_mul_f32 v[172:173], v[174:175], v[174:175]
	v_cvt_pk_bf16_f32 v170, v159, v165
	v_cvt_pk_bf16_f32 v171, v166, v167
	global_store_dwordx4 v[178:179], v[168:171], off
	v_pk_mul_f32 v[172:173], v[172:173], s[58:59] op_sel_hi:[1,0]
	v_cmp_gt_f32_e32 vcc, 0, v174
	v_pk_fma_f32 v[168:169], v[176:177], s[42:43], v[154:155] op_sel_hi:[1,0,0]
	v_pk_mul_f32 v[170:171], v[116:117], v[148:149] op_sel_hi:[1,0]
	v_pk_fma_f32 v[168:169], v[176:177], v[168:169], s[52:53] op_sel_hi:[1,1,0]
	v_exp_f32_e32 v172, v172
	v_exp_f32_e32 v173, v173
	v_pk_fma_f32 v[168:169], v[176:177], v[168:169], s[54:55] op_sel_hi:[1,1,0]
	v_pk_fma_f32 v[168:169], v[176:177], v[168:169], s[56:57] op_sel_hi:[1,1,0]
	v_fma_f32 v180, |v170|, s40, 1.0
; __device__ __forceinline__ float dot4(f32x4 v) { return (v[0] * v[0] + v[1] * v[1]) + (v[2] * v[2] + v[3] * v[3]); }
; __device__ __forceinline__ u32x2 pack4(f32x4 v) { u32x2 w; w.x = cvt_pk_bf16(v[0], v[1]); w.y = cvt_pk_bf16(v[2], v[3]); return w; }
; __device__ __forceinline__ float quad_sum(float s) { s += __shfl_xor(s, 16); s += __shfl_xor(s, 32); return s; }
; __device__ __forceinline__ f32x4 gelu4(f32x4 v) { f32x2 a = gelu_pk((f32x2){v[0], v[1]}), b = gelu_pk((f32x2){v[2], v[3]}); return (f32x4){a.x, a.y, b.x, b.y}; }
; __device__ __forceinline__ f32x2 gelu_pk(f32x2 v) {
;     const f32x2 av = __builtin_elementwise_abs(v), d = av * 0.2316418882f + 1.0f;
;     f32x2 t; t.x = __builtin_amdgcn_rcpf(d.x); t.y = __builtin_amdgcn_rcpf(d.y);
;     f32x2 q = t * 0.5307027145f + (-0.7265760135f); q = q * t + 0.7107068705f; q = q * t + (-0.142248368f); q = q * t + 0.127414796f; q = q * t;
;     const f32x2 s = (v * v) * (-0.72134752044f);
;     f32x2 e; e.x = __builtin_amdgcn_exp2f(s.x); e.y = __builtin_amdgcn_exp2f(s.y);
;     const f32x2 m = v * (q * e), r = v - m;
;     f32x2 o; o.x = v.x < 0.f ? m.x : r.x; o.y = v.y < 0.f ? m.y : r.y; return o;
; template <int EK>
; __device__ __forceinline__ void epi_tile(const f32x4 (&acc)[2][2][4][2], const Unit& u, int wr, int wc, int fr, int fq, const EpiArgs& E, const LAS float* rt) {
;     ...
;                 for (int bj = 0; bj < 2; ++bj) { const int col = u.pn * BM + bj * HALF + wc * 32 + fq * 8;
;                     const f32x4 z0 = gelu4(acc[ai][bj][m][0] * r), z1 = gelu4(acc[ai][bj][m][1] * r); ss += dot4(z0) + dot4(z1);
;                     const u32x2 lo = pack4(z0), hi = pack4(z1);
;                     *(u32x4*)(E.ob + (size_t)row * E.ldb + col) = (u32x4){lo.x, lo.y, hi.x, hi.y}; }
;                 if (u.pn >= 4) { ss = quad_sum(ss); if (fq == 0) E.stOut[(size_t)row * 16 + (u.pn - 4) * 4 + wc] = ss; }
	v_fma_f32 v181, |v171|, s40, 1.0
	v_pk_mul_f32 v[168:169], v[176:177], v[168:169]
	v_rcp_f32_e32 v180, v180
	v_rcp_f32_e32 v181, v181
	v_pk_mul_f32 v[168:169], v[172:173], v[168:169]
	v_pk_mul_f32 v[176:177], v[170:171], v[170:171]
	v_pk_mul_f32 v[172:173], v[174:175], v[168:169]
	v_pk_fma_f32 v[168:169], v[174:175], v[168:169], v[174:175] neg_lo:[1,0,0] neg_hi:[1,0,0]
	s_nop 0
	v_cndmask_b32_e32 v168, v168, v172, vcc
	v_cmp_gt_f32_e32 vcc, 0, v175
	v_pk_mul_f32 v[174:175], v[176:177], s[58:59] op_sel_hi:[1,0]
	v_pk_mul_f32 v[176:177], v[118:119], v[148:149] op_sel_hi:[1,0]
	v_cndmask_b32_e32 v169, v169, v173, vcc
	v_pk_fma_f32 v[172:173], v[180:181], s[42:43], v[154:155] op_sel_hi:[1,0,0]
	v_exp_f32_e32 v174, v174
	v_pk_fma_f32 v[172:173], v[180:181], v[172:173], s[52:53] op_sel_hi:[1,1,0]
	v_exp_f32_e32 v175, v175
	v_pk_fma_f32 v[172:173], v[180:181], v[172:173], s[54:55] op_sel_hi:[1,1,0]
	v_pk_fma_f32 v[172:173], v[180:181], v[172:173], s[56:57] op_sel_hi:[1,1,0]
	v_pk_mul_f32 v[182:183], v[176:177], v[176:177]
	v_pk_mul_f32 v[172:173], v[180:181], v[172:173]
	v_fma_f32 v180, |v176|, s40, 1.0
	v_fma_f32 v181, |v177|, s40, 1.0
	v_pk_mul_f32 v[172:173], v[174:175], v[172:173]
	v_rcp_f32_e32 v180, v180
	v_rcp_f32_e32 v181, v181
	v_max_f32_e32 v174, 0, v170
	v_max_f32_e32 v175, 0, v171
	v_fma_f32 v170, -|v170|, v172, v174
	v_fma_f32 v171, -|v171|, v173, v175
	v_pk_mul_f32 v[182:183], v[182:183], s[58:59] op_sel_hi:[1,0]
	v_exp_f32_e32 v182, v182
	v_exp_f32_e32 v183, v183
	v_pk_mul_f32 v[174:175], v[120:121], v[148:149] op_sel_hi:[1,0]
	v_pk_fma_f32 v[172:173], v[180:181], s[42:43], v[154:155] op_sel_hi:[1,0,0]
	v_pk_fma_f32 v[172:173], v[180:181], v[172:173], s[52:53] op_sel_hi:[1,1,0]
	v_pk_fma_f32 v[172:173], v[180:181], v[172:173], s[54:55] op_sel_hi:[1,1,0]
	v_fma_f32 v184, |v174|, s40, 1.0
	v_fma_f32 v185, |v175|, s40, 1.0
	v_pk_fma_f32 v[172:173], v[180:181], v[172:173], s[56:57] op_sel_hi:[1,1,0]
	v_rcp_f32_e32 v184, v184
	v_rcp_f32_e32 v185, v185
	v_pk_mul_f32 v[172:173], v[180:181], v[172:173]
	v_pk_mul_f32 v[180:181], v[174:175], v[174:175]
	v_pk_mul_f32 v[172:173], v[182:183], v[172:173]
	v_max_f32_e32 v182, 0, v176
	v_max_f32_e32 v183, 0, v177
	v_fma_f32 v148, -|v176|, v172, v182
	v_fma_f32 v172, -|v177|, v173, v183
	v_pk_fma_f32 v[154:155], v[184:185], s[42:43], v[154:155] op_sel_hi:[1,0,0]
	v_pk_mul_f32 v[176:177], v[180:181], s[58:59] op_sel_hi:[1,0]
	v_pk_fma_f32 v[154:155], v[184:185], v[154:155], s[52:53] op_sel_hi:[1,1,0]
	v_exp_f32_e32 v176, v176
	v_exp_f32_e32 v177, v177
	v_pk_fma_f32 v[154:155], v[184:185], v[154:155], s[54:55] op_sel_hi:[1,1,0]
	v_pk_fma_f32 v[154:155], v[184:185], v[154:155], s[56:57] op_sel_hi:[1,1,0]
	v_pk_mul_f32 v[154:155], v[184:185], v[154:155]
	s_nop 0
	v_pk_mul_f32 v[154:155], v[176:177], v[154:155]
	s_nop 0
	v_max_f32_e32 v176, 0, v174
	v_max_f32_e32 v177, 0, v175
	v_fma_f32 v154, -|v174|, v154, v176
	v_fma_f32 v155, -|v175|, v155, v177
	v_cvt_pk_bf16_f32 v174, v168, v169
	s_nop 0
	v_cvt_pk_bf16_f32 v175, v170, v171
	v_cvt_pk_bf16_f32 v176, v148, v172
	s_nop 1
	s_and_b64 vcc, exec, s[10:11]
	v_cvt_pk_bf16_f32 v177, v154, v155
	global_store_dwordx4 v[178:179], v[174:177], off offset:256
	s_cbranch_vccnz .LBB0_960
	v_mul_f32_e32 v156, v156, v156
	v_fmac_f32_e32 v156, v151, v151
	v_mul_f32_e32 v151, v158, v158
	v_fmac_f32_e32 v151, v157, v157
	v_add_f32_e32 v151, v156, v151
	v_mul_f32_e32 v156, v165, v165
	v_mul_f32_e32 v157, v167, v167
	v_fmac_f32_e32 v156, v159, v159
	v_fmac_f32_e32 v157, v166, v166
	v_add_f32_e32 v156, v156, v157
	v_add_f32_e32 v151, v151, v156
	v_mul_f32_e32 v156, v169, v169
	v_mul_f32_e32 v157, v171, v171
	v_fmac_f32_e32 v156, v168, v168
	v_fmac_f32_e32 v157, v170, v170
	v_add_f32_e32 v156, v156, v157
	v_mul_f32_e32 v157, v172, v172
	v_fmac_f32_e32 v157, v148, v148
	v_mul_f32_e32 v148, v155, v155
	v_fmac_f32_e32 v148, v154, v154
	v_add_f32_e32 v148, v157, v148
	v_add_f32_e32 v148, v156, v148
	v_and_b32_e32 v154, 64, v164
	v_add_f32_e32 v148, v151, v148
	v_xor_b32_e32 v151, 16, v164
	v_add_u32_e32 v154, 64, v154
	v_cmp_lt_i32_e32 vcc, v151, v154
	s_nop 1
	v_cndmask_b32_e32 v151, v164, v151, vcc
	v_lshlrev_b32_e32 v151, 2, v151
	ds_bpermute_b32 v151, v151, v148
	s_waitcnt lgkmcnt(0)
	v_add_f32_e32 v148, v148, v151
	v_xor_b32_e32 v151, 32, v164
	v_cmp_lt_i32_e32 vcc, v151, v154
	s_nop 1
	v_cndmask_b32_e32 v151, v164, v151, vcc
	v_lshlrev_b32_e32 v151, 2, v151
	ds_bpermute_b32 v151, v151, v148
	s_and_saveexec_b64 s[78:79], s[4:5]
	s_cbranch_execz .LBB0_959
	v_lshlrev_b64 v[152:153], 6, v[152:153]
	v_lshl_add_u64 v[152:153], s[18:19], 0, v[152:153]
	v_lshl_add_u64 v[152:153], s[76:77], 2, v[152:153]
	s_lshl_b32 s14, s59, 2
	v_lshl_add_u64 v[152:153], v[152:153], 0, s[14:15]
	s_waitcnt lgkmcnt(0)
	v_add_f32_e32 v148, v148, v151
	global_store_dword v[152:153], v148, off

; __device__ __forceinline__ float dot4(f32x4 v) { return (v[0] * v[0] + v[1] * v[1]) + (v[2] * v[2] + v[3] * v[3]); }
; __device__ __forceinline__ u32x2 pack4(f32x4 v) { u32x2 w; w.x = cvt_pk_bf16(v[0], v[1]); w.y = cvt_pk_bf16(v[2], v[3]); return w; }
; __device__ __forceinline__ f32x4 gelu4(f32x4 v) { f32x2 a = gelu_pk((f32x2){v[0], v[1]}), b = gelu_pk((f32x2){v[2], v[3]}); return (f32x4){a.x, a.y, b.x, b.y}; }
; __device__ __forceinline__ f32x2 gelu_pk(f32x2 v) {
;     const f32x2 av = __builtin_elementwise_abs(v), d = av * 0.2316418882f + 1.0f;
;     f32x2 t; t.x = __builtin_amdgcn_rcpf(d.x); t.y = __builtin_amdgcn_rcpf(d.y);
;     f32x2 q = t * 0.5307027145f + (-0.7265760135f); q = q * t + 0.7107068705f; q = q * t + (-0.142248368f); q = q * t + 0.127414796f; q = q * t;
;     const f32x2 s = (v * v) * (-0.72134752044f);
;     f32x2 e; e.x = __builtin_amdgcn_exp2f(s.x); e.y = __builtin_amdgcn_exp2f(s.y);
;     const f32x2 m = v * (q * e), r = v - m;
;     f32x2 o; o.x = v.x < 0.f ? m.x : r.x; o.y = v.y < 0.f ? m.y : r.y; return o;
; template <int EK>
; __device__ __forceinline__ void epi_tile(const f32x4 (&acc)[2][2][4][2], const Unit& u, int wr, int wc, int fr, int fq, const EpiArgs& E, const LAS float* rt) {
;     ...
;             } else if (EK == EK_GELU) {
;                 const float r = rr[ai][m]; float ss = 0.f;
; #pragma unroll
;                 for (int bj = 0; bj < 2; ++bj) { const int col = u.pn * BM + bj * HALF + wc * 32 + fq * 8;
;                     const f32x4 z0 = gelu4(acc[ai][bj][m][0] * r), z1 = gelu4(acc[ai][bj][m][1] * r); ss += dot4(z0) + dot4(z1);
;                     const u32x2 lo = pack4(z0), hi = pack4(z1);
;                     *(u32x4*)(E.ob + (size_t)row * E.ldb + col) = (u32x4){lo.x, lo.y, hi.x, hi.y}; }
.LBB0_960:
	v_mov_b32_e32 v170, v149
	v_pk_mul_f32 v[152:153], v[22:23], v[170:171] op_sel_hi:[1,0]
	v_add_u32_e32 v148, 0xb0, v150
	s_waitcnt lgkmcnt(0)
	v_fma_f32 v150, |v152|, s40, 1.0
	v_fma_f32 v151, |v153|, s40, 1.0
	v_pk_mul_f32 v[166:167], v[152:153], v[152:153]
	v_rcp_f32_e32 v154, v150
	v_rcp_f32_e32 v155, v151
	v_mov_b64_e32 v[150:151], s[44:45]
	v_pk_mul_f32 v[166:167], v[166:167], s[58:59] op_sel_hi:[1,0]
	v_pk_mul_f32 v[156:157], v[24:25], v[170:171] op_sel_hi:[1,0]
	v_pk_fma_f32 v[158:159], v[154:155], s[42:43], v[150:151] op_sel_hi:[1,0,0]
	v_exp_f32_e32 v166, v166
	v_pk_fma_f32 v[158:159], v[154:155], v[158:159], s[52:53] op_sel_hi:[1,1,0]
	v_exp_f32_e32 v167, v167
	v_pk_fma_f32 v[158:159], v[154:155], v[158:159], s[54:55] op_sel_hi:[1,1,0]
	v_pk_fma_f32 v[158:159], v[154:155], v[158:159], s[56:57] op_sel_hi:[1,1,0]
	v_fma_f32 v168, |v156|, s40, 1.0
	v_fma_f32 v169, |v157|, s40, 1.0
	v_pk_mul_f32 v[154:155], v[154:155], v[158:159]
	v_rcp_f32_e32 v168, v168
	v_rcp_f32_e32 v169, v169
	v_pk_mul_f32 v[154:155], v[166:167], v[154:155]
	v_max_f32_e32 v166, 0, v152
	v_max_f32_e32 v167, 0, v153
	v_fma_f32 v152, -|v152|, v154, v166
	v_fma_f32 v153, -|v153|, v155, v167
	v_pk_mul_f32 v[158:159], v[156:157], v[156:157]
	v_pk_mul_f32 v[158:159], v[158:159], s[58:59] op_sel_hi:[1,0]
	v_ashrrev_i32_e32 v149, 31, v148
	v_pk_fma_f32 v[154:155], v[168:169], s[42:43], v[150:151] op_sel_hi:[1,0,0]
	v_exp_f32_e32 v158, v158
	v_pk_fma_f32 v[154:155], v[168:169], v[154:155], s[52:53] op_sel_hi:[1,1,0]
	v_exp_f32_e32 v159, v159
	v_pk_fma_f32 v[154:155], v[168:169], v[154:155], s[54:55] op_sel_hi:[1,1,0]
	v_pk_mul_f32 v[166:167], v[18:19], v[170:171] op_sel_hi:[1,0]
	v_pk_fma_f32 v[154:155], v[168:169], v[154:155], s[56:57] op_sel_hi:[1,1,0]
	v_pk_mul_f32 v[154:155], v[168:169], v[154:155]
	v_fma_f32 v168, |v166|, s40, 1.0
	v_fma_f32 v169, |v167|, s40, 1.0
	v_pk_mul_f32 v[154:155], v[158:159], v[154:155]
	v_rcp_f32_e32 v168, v168
	v_rcp_f32_e32 v169, v169
	v_max_f32_e32 v158, 0, v156
	v_max_f32_e32 v159, 0, v157
	v_fma_f32 v154, -|v156|, v154, v158
	v_fma_f32 v155, -|v157|, v155, v159
	v_pk_mul_f32 v[172:173], v[166:167], v[166:167]
	v_pk_fma_f32 v[156:157], v[168:169], s[42:43], v[150:151] op_sel_hi:[1,0,0]
	v_pk_mul_f32 v[172:173], v[172:173], s[58:59] op_sel_hi:[1,0]
	v_pk_mul_f32 v[158:159], v[20:21], v[170:171] op_sel_hi:[1,0]
	v_pk_fma_f32 v[156:157], v[168:169], v[156:157], s[52:53] op_sel_hi:[1,1,0]
	v_exp_f32_e32 v172, v172
	v_exp_f32_e32 v173, v173
	v_pk_fma_f32 v[156:157], v[168:169], v[156:157], s[54:55] op_sel_hi:[1,1,0]
	v_fma_f32 v174, |v158|, s40, 1.0
	v_fma_f32 v175, |v159|, s40, 1.0
	v_pk_fma_f32 v[156:157], v[168:169], v[156:157], s[56:57] op_sel_hi:[1,1,0]
	v_rcp_f32_e32 v174, v174
	v_rcp_f32_e32 v175, v175
	v_pk_mul_f32 v[156:157], v[168:169], v[156:157]
	v_pk_mul_f32 v[156:157], v[172:173], v[156:157]
	v_pk_mul_f32 v[168:169], v[158:159], v[158:159]
	v_max_f32_e32 v172, 0, v166
	v_max_f32_e32 v173, 0, v167
	v_fma_f32 v156, -|v166|, v156, v172
	v_fma_f32 v157, -|v167|, v157, v173
	v_pk_mul_f32 v[168:169], v[168:169], s[58:59] op_sel_hi:[1,0]
	v_pk_fma_f32 v[166:167], v[174:175], s[42:43], v[150:151] op_sel_hi:[1,0,0]
	v_exp_f32_e32 v168, v168
	v_pk_fma_f32 v[166:167], v[174:175], v[166:167], s[52:53] op_sel_hi:[1,1,0]
	v_exp_f32_e32 v169, v169
	v_pk_fma_f32 v[166:167], v[174:175], v[166:167], s[54:55] op_sel_hi:[1,1,0]
	v_pk_fma_f32 v[166:167], v[174:175], v[166:167], s[56:57] op_sel_hi:[1,1,0]
	v_pk_mul_f32 v[166:167], v[174:175], v[166:167]
	v_pk_mul_f32 v[174:175], v[122:123], v[170:171] op_sel_hi:[1,0]
	v_pk_mul_f32 v[166:167], v[168:169], v[166:167]
	v_fma_f32 v176, |v174|, s40, 1.0
	v_fma_f32 v177, |v175|, s40, 1.0
	v_rcp_f32_e32 v176, v176
	v_rcp_f32_e32 v177, v177
	v_max_f32_e32 v168, 0, v158
	v_max_f32_e32 v169, 0, v159
	v_fma_f32 v158, -|v158|, v166, v168
	v_fma_f32 v159, -|v159|, v167, v169
	v_lshlrev_b64 v[172:173], 12, v[148:149]
	v_lshl_add_u64 v[172:173], s[64:65], 0, v[172:173]
	v_cvt_pk_bf16_f32 v168, v156, v157
	v_lshl_add_u64 v[178:179], v[146:147], 1, v[172:173]
	v_cvt_pk_bf16_f32 v169, v158, v159
	v_pk_fma_f32 v[146:147], v[176:177], s[42:43], v[150:151] op_sel_hi:[1,0,0]
	v_cvt_pk_bf16_f32 v166, v152, v153
	v_cvt_pk_bf16_f32 v167, v154, v155
	global_store_dwordx4 v[178:179], v[166:169], off
	v_pk_fma_f32 v[146:147], v[176:177], v[146:147], s[52:53] op_sel_hi:[1,1,0]
	v_cmp_gt_f32_e32 vcc, 0, v174
	v_pk_mul_f32 v[168:169], v[174:175], v[174:175]
	v_pk_fma_f32 v[146:147], v[176:177], v[146:147], s[54:55] op_sel_hi:[1,1,0]
	v_pk_mul_f32 v[168:169], v[168:169], s[58:59] op_sel_hi:[1,0]
	v_pk_mul_f32 v[166:167], v[124:125], v[170:171] op_sel_hi:[1,0]
	v_exp_f32_e32 v168, v168
	v_exp_f32_e32 v169, v169
	v_pk_fma_f32 v[146:147], v[176:177], v[146:147], s[56:57] op_sel_hi:[1,1,0]
	v_pk_mul_f32 v[172:173], v[166:167], v[166:167]
; __device__ __forceinline__ float dot4(f32x4 v) { return (v[0] * v[0] + v[1] * v[1]) + (v[2] * v[2] + v[3] * v[3]); }
; __device__ __forceinline__ u32x2 pack4(f32x4 v) { u32x2 w; w.x = cvt_pk_bf16(v[0], v[1]); w.y = cvt_pk_bf16(v[2], v[3]); return w; }
; __device__ __forceinline__ float quad_sum(float s) { s += __shfl_xor(s, 16); s += __shfl_xor(s, 32); return s; }
; __device__ __forceinline__ f32x4 gelu4(f32x4 v) { f32x2 a = gelu_pk((f32x2){v[0], v[1]}), b = gelu_pk((f32x2){v[2], v[3]}); return (f32x4){a.x, a.y, b.x, b.y}; }
; __device__ __forceinline__ f32x2 gelu_pk(f32x2 v) {
;     const f32x2 av = __builtin_elementwise_abs(v), d = av * 0.2316418882f + 1.0f;
;     f32x2 t; t.x = __builtin_amdgcn_rcpf(d.x); t.y = __builtin_amdgcn_rcpf(d.y);
;     f32x2 q = t * 0.5307027145f + (-0.7265760135f); q = q * t + 0.7107068705f; q = q * t + (-0.142248368f); q = q * t + 0.127414796f; q = q * t;
;     const f32x2 s = (v * v) * (-0.72134752044f);
;     f32x2 e; e.x = __builtin_amdgcn_exp2f(s.x); e.y = __builtin_amdgcn_exp2f(s.y);
;     const f32x2 m = v * (q * e), r = v - m;
;     f32x2 o; o.x = v.x < 0.f ? m.x : r.x; o.y = v.y < 0.f ? m.y : r.y; return o;
; template <int EK>
; __device__ __forceinline__ void epi_tile(const f32x4 (&acc)[2][2][4][2], const Unit& u, int wr, int wc, int fr, int fq, const EpiArgs& E, const LAS float* rt) {
;     ...
;                 for (int bj = 0; bj < 2; ++bj) { const int col = u.pn * BM + bj * HALF + wc * 32 + fq * 8;
;                     const f32x4 z0 = gelu4(acc[ai][bj][m][0] * r), z1 = gelu4(acc[ai][bj][m][1] * r); ss += dot4(z0) + dot4(z1);
;                     const u32x2 lo = pack4(z0), hi = pack4(z1);
;                     *(u32x4*)(E.ob + (size_t)row * E.ldb + col) = (u32x4){lo.x, lo.y, hi.x, hi.y}; }
;                 if (u.pn >= 4) { ss = quad_sum(ss); if (fq == 0) E.stOut[(size_t)row * 16 + (u.pn - 4) * 4 + wc] = ss; }
	v_pk_mul_f32 v[146:147], v[176:177], v[146:147]
	v_fma_f32 v176, |v166|, s40, 1.0
	v_fma_f32 v177, |v167|, s40, 1.0
	v_pk_mul_f32 v[146:147], v[168:169], v[146:147]
	v_rcp_f32_e32 v176, v176
	v_rcp_f32_e32 v177, v177
	v_pk_mul_f32 v[168:169], v[174:175], v[146:147]
	v_pk_fma_f32 v[146:147], v[174:175], v[146:147], v[174:175] neg_lo:[1,0,0] neg_hi:[1,0,0]
	v_pk_mul_f32 v[172:173], v[172:173], s[58:59] op_sel_hi:[1,0]
	v_cndmask_b32_e32 v146, v146, v168, vcc
	v_cmp_gt_f32_e32 vcc, 0, v175
	v_exp_f32_e32 v172, v172
	v_exp_f32_e32 v173, v173
	v_cndmask_b32_e32 v147, v147, v169, vcc
	v_pk_fma_f32 v[168:169], v[176:177], s[42:43], v[150:151] op_sel_hi:[1,0,0]
	v_pk_mul_f32 v[174:175], v[126:127], v[170:171] op_sel_hi:[1,0]
	v_pk_fma_f32 v[168:169], v[176:177], v[168:169], s[52:53] op_sel_hi:[1,1,0]
	v_pk_fma_f32 v[168:169], v[176:177], v[168:169], s[54:55] op_sel_hi:[1,1,0]
	v_pk_mul_f32 v[170:171], v[128:129], v[170:171] op_sel_hi:[1,0]
	v_pk_fma_f32 v[168:169], v[176:177], v[168:169], s[56:57] op_sel_hi:[1,1,0]
	v_pk_mul_f32 v[168:169], v[176:177], v[168:169]
	v_fma_f32 v176, |v174|, s40, 1.0
	v_fma_f32 v177, |v175|, s40, 1.0
	v_pk_mul_f32 v[168:169], v[172:173], v[168:169]
	v_rcp_f32_e32 v176, v176
	v_rcp_f32_e32 v177, v177
	v_max_f32_e32 v172, 0, v166
	v_max_f32_e32 v173, 0, v167
	v_fma_f32 v165, -|v166|, v168, v172
	v_fma_f32 v166, -|v167|, v169, v173
	v_fma_f32 v180, |v170|, s40, 1.0
	v_fma_f32 v181, |v171|, s40, 1.0
	s_nop 0
	v_pk_mul_f32 v[172:173], v[174:175], v[174:175]
	v_pk_fma_f32 v[168:169], v[176:177], s[42:43], v[150:151] op_sel_hi:[1,0,0]
	v_pk_mul_f32 v[172:173], v[172:173], s[58:59] op_sel_hi:[1,0]
	v_pk_fma_f32 v[168:169], v[176:177], v[168:169], s[52:53] op_sel_hi:[1,1,0]
	v_exp_f32_e32 v172, v172
	v_exp_f32_e32 v173, v173
	v_pk_fma_f32 v[168:169], v[176:177], v[168:169], s[54:55] op_sel_hi:[1,1,0]
	v_rcp_f32_e32 v180, v180
	v_pk_fma_f32 v[168:169], v[176:177], v[168:169], s[56:57] op_sel_hi:[1,1,0]
	v_rcp_f32_e32 v181, v181
	v_pk_mul_f32 v[168:169], v[176:177], v[168:169]
	v_pk_mul_f32 v[168:169], v[172:173], v[168:169]
	v_pk_mul_f32 v[176:177], v[170:171], v[170:171]
	v_max_f32_e32 v172, 0, v174
	v_max_f32_e32 v173, 0, v175
	v_fma_f32 v167, -|v174|, v168, v172
	v_fma_f32 v168, -|v175|, v169, v173
	v_pk_fma_f32 v[150:151], v[180:181], s[42:43], v[150:151] op_sel_hi:[1,0,0]
	v_pk_fma_f32 v[150:151], v[180:181], v[150:151], s[52:53] op_sel_hi:[1,1,0]
	s_nop 0
	v_pk_mul_f32 v[172:173], v[176:177], s[58:59] op_sel_hi:[1,0]
	v_pk_fma_f32 v[150:151], v[180:181], v[150:151], s[54:55] op_sel_hi:[1,1,0]
	v_exp_f32_e32 v172, v172
	v_exp_f32_e32 v173, v173
	v_pk_fma_f32 v[150:151], v[180:181], v[150:151], s[56:57] op_sel_hi:[1,1,0]
	v_pk_mul_f32 v[150:151], v[180:181], v[150:151]
	s_nop 0
	v_pk_mul_f32 v[150:151], v[172:173], v[150:151]
	s_nop 0
	v_max_f32_e32 v172, 0, v170
	v_max_f32_e32 v173, 0, v171
	v_fma_f32 v150, -|v170|, v150, v172
	v_fma_f32 v151, -|v171|, v151, v173
	v_cvt_pk_bf16_f32 v170, v146, v147
	s_nop 0
	v_cvt_pk_bf16_f32 v171, v165, v166
	v_cvt_pk_bf16_f32 v172, v167, v168
	s_nop 1
	s_and_b64 vcc, exec, s[10:11]
	v_cvt_pk_bf16_f32 v173, v150, v151
	global_store_dwordx4 v[178:179], v[170:173], off offset:256
	s_cbranch_vccnz .LBB0_964
	v_mul_f32_e32 v147, v147, v147
	v_fmac_f32_e32 v147, v146, v146
	v_mul_f32_e32 v146, v166, v166
	v_mul_f32_e32 v153, v153, v153
	v_fmac_f32_e32 v146, v165, v165
	v_fmac_f32_e32 v153, v152, v152
	v_mul_f32_e32 v152, v155, v155
	v_add_f32_e32 v146, v147, v146
	v_mul_f32_e32 v147, v168, v168
	v_mul_f32_e32 v151, v151, v151
	v_fmac_f32_e32 v152, v154, v154
	v_fmac_f32_e32 v147, v167, v167
	v_fmac_f32_e32 v151, v150, v150
	v_add_f32_e32 v152, v153, v152
	v_mul_f32_e32 v153, v157, v157
	v_mul_f32_e32 v154, v159, v159
	v_add_f32_e32 v147, v147, v151
	v_and_b32_e32 v150, 64, v164
	v_fmac_f32_e32 v153, v156, v156
	v_fmac_f32_e32 v154, v158, v158
	v_add_f32_e32 v146, v146, v147
	v_xor_b32_e32 v147, 16, v164
	v_add_u32_e32 v150, 64, v150
	v_add_f32_e32 v153, v153, v154
	v_cmp_lt_i32_e32 vcc, v147, v150
	v_add_f32_e32 v152, v152, v153
	v_add_f32_e32 v146, v152, v146
	v_cndmask_b32_e32 v147, v164, v147, vcc
	v_lshlrev_b32_e32 v147, 2, v147
	ds_bpermute_b32 v147, v147, v146
	s_waitcnt lgkmcnt(0)
	v_add_f32_e32 v146, v146, v147
	v_xor_b32_e32 v147, 32, v164
	v_cmp_lt_i32_e32 vcc, v147, v150
	s_nop 1
	v_cndmask_b32_e32 v147, v164, v147, vcc
	v_lshlrev_b32_e32 v147, 2, v147
	ds_bpermute_b32 v147, v147, v146
	s_and_saveexec_b64 s[10:11], s[4:5]
	s_cbranch_execz .LBB0_963
	v_lshlrev_b64 v[148:149], 6, v[148:149]
	v_lshl_add_u64 v[148:149], s[18:19], 0, v[148:149]
	v_lshl_add_u64 v[148:149], s[76:77], 2, v[148:149]
	s_lshl_b32 s14, s59, 2
	v_lshl_add_u64 v[148:149], v[148:149], 0, s[14:15]
	s_waitcnt lgkmcnt(0)
	v_add_f32_e32 v146, v146, v147
	global_store_dword v[148:149], v146, off
